# v2 + GEMM K-loops: first iteration peeled with SrcC=0, per-unit 128 v_mov accumulator zero-inits removed
# speedup vs baseline: 1.0084x; 1.0084x over previous
.LBB0_228:
	s_ashr_i32 s21, s20, 31
	s_lshl_b64 s[22:23], s[20:21], 21
	s_add_u32 s22, s35, s22
	s_addc_u32 s23, s38, s23
	s_and_b64 s[24:25], s[4:5], exec
	s_cselect_b32 s21, s23, s29
	s_cselect_b32 s59, s22, s28
	s_ashr_i32 s19, s18, 31
	s_lshl_b64 s[24:25], s[18:19], 21
	s_add_u32 s24, s39, s24
	s_addc_u32 s25, s45, s25
	s_and_b64 s[36:37], s[4:5], exec
	s_cselect_b32 s19, s25, s31
	s_cselect_b32 s60, s24, s30
	s_add_u32 s28, s28, 0x100080
	s_addc_u32 s29, s29, 0
	s_add_u32 s61, s30, 0x100
	s_addc_u32 s62, s31, 0
	s_mov_b32 s67, -2
	ds_read_b128 v[144:147], v149
	ds_read_b128 v[154:157], v149 offset:1024
	ds_read_b128 v[158:161], v149 offset:2048
	ds_read_b128 v[162:165], v149 offset:3072
	ds_read_b128 v[166:169], v150
	ds_read_b128 v[170:173], v150 offset:1024
	ds_read_b128 v[174:177], v150 offset:2048
	ds_read_b128 v[178:181], v150 offset:3072
	s_add_u32 s30, s28, 0xfff00080
	s_addc_u32 s31, s29, -1
	s_cmp_eq_u32 s67, 60
	s_cselect_b32 s37, s21, s31
	s_cselect_b32 s36, s59, s30
	s_cselect_b32 s31, s19, s62
	s_cselect_b32 s30, s60, s61
	v_lshl_add_u64 v[214:215], s[28:29], 0, v[136:137]
	s_add_i32 m0, s27, 0xc000
	ds_read_b128 v[182:185], v151
	ds_read_b128 v[186:189], v151 offset:1024
	ds_read_b128 v[190:193], v151 offset:2048
	ds_read_b128 v[194:197], v151 offset:3072
	ds_read_b128 v[198:201], v151 offset:4096
	ds_read_b128 v[202:205], v151 offset:5120
	ds_read_b128 v[206:209], v151 offset:6144
	ds_read_b128 v[210:213], v151 offset:7168
	global_load_lds_dwordx4 v[214:215], off
	v_lshl_add_u64 v[214:215], s[28:29], 0, v[138:139]
	s_add_i32 m0, s27, 0xe000
	s_nop 0
	global_load_lds_dwordx4 v[214:215], off
	s_waitcnt vmcnt(8)
	s_waitcnt lgkmcnt(0)
	s_barrier
	s_setprio 1
	s_waitcnt lgkmcnt(0)
	v_mfma_f32_16x16x32_bf16 v[124:127], v[144:147], v[182:185], 0
	v_mfma_f32_16x16x32_bf16 v[120:123], v[158:161], v[182:185], 0
	v_mfma_f32_16x16x32_bf16 v[112:115], v[144:147], v[190:193], 0
	v_mfma_f32_16x16x32_bf16 v[104:107], v[158:161], v[190:193], 0
	v_mfma_f32_16x16x32_bf16 v[96:99], v[144:147], v[198:201], 0
	v_mfma_f32_16x16x32_bf16 v[88:91], v[158:161], v[198:201], 0
	v_mfma_f32_16x16x32_bf16 v[80:83], v[144:147], v[206:209], 0
	v_mfma_f32_16x16x32_bf16 v[72:75], v[158:161], v[206:209], 0
	v_mfma_f32_16x16x32_bf16 v[124:127], v[154:157], v[186:189], v[124:127]
	v_mfma_f32_16x16x32_bf16 v[120:123], v[162:165], v[186:189], v[120:123]
	v_mfma_f32_16x16x32_bf16 v[112:115], v[154:157], v[194:197], v[112:115]
	v_mfma_f32_16x16x32_bf16 v[104:107], v[162:165], v[194:197], v[104:107]
	v_mfma_f32_16x16x32_bf16 v[96:99], v[154:157], v[202:205], v[96:99]
	v_mfma_f32_16x16x32_bf16 v[88:91], v[162:165], v[202:205], v[88:91]
	v_mfma_f32_16x16x32_bf16 v[80:83], v[154:157], v[210:213], v[80:83]
	v_mfma_f32_16x16x32_bf16 v[72:75], v[162:165], v[210:213], v[72:75]
	s_setprio 0
	s_setprio 1
	v_mfma_f32_16x16x32_bf16 v[116:119], v[166:169], v[182:185], 0
	v_mfma_f32_16x16x32_bf16 v[108:111], v[174:177], v[182:185], 0
	v_mfma_f32_16x16x32_bf16 v[100:103], v[166:169], v[190:193], 0
	v_mfma_f32_16x16x32_bf16 v[92:95], v[174:177], v[190:193], 0
	v_mfma_f32_16x16x32_bf16 v[84:87], v[166:169], v[198:201], 0
	v_mfma_f32_16x16x32_bf16 v[76:79], v[174:177], v[198:201], 0
	v_mfma_f32_16x16x32_bf16 v[68:71], v[166:169], v[206:209], 0
	v_mfma_f32_16x16x32_bf16 v[64:67], v[174:177], v[206:209], 0
	v_mfma_f32_16x16x32_bf16 v[116:119], v[170:173], v[186:189], v[116:119]
	v_mfma_f32_16x16x32_bf16 v[108:111], v[178:181], v[186:189], v[108:111]
	v_mfma_f32_16x16x32_bf16 v[100:103], v[170:173], v[194:197], v[100:103]
	v_mfma_f32_16x16x32_bf16 v[92:95], v[178:181], v[194:197], v[92:95]
	v_mfma_f32_16x16x32_bf16 v[84:87], v[170:173], v[202:205], v[84:87]
	v_mfma_f32_16x16x32_bf16 v[76:79], v[178:181], v[202:205], v[76:79]
	v_mfma_f32_16x16x32_bf16 v[68:71], v[170:173], v[210:213], v[68:71]
	v_mfma_f32_16x16x32_bf16 v[64:67], v[178:181], v[210:213], v[64:67]
	s_setprio 0
	s_barrier
	s_add_i32 s68, s56, s46
	v_lshl_add_u64 v[214:215], s[30:31], 0, v[130:131]
	s_mov_b32 m0, s68
	ds_read_b128 v[182:185], v151 offset:16384
	ds_read_b128 v[186:189], v151 offset:17408
	ds_read_b128 v[190:193], v151 offset:18432
	ds_read_b128 v[194:197], v151 offset:19456
	ds_read_b128 v[198:201], v151 offset:20480
	ds_read_b128 v[202:205], v151 offset:21504
	ds_read_b128 v[206:209], v151 offset:22528
	ds_read_b128 v[210:213], v151 offset:23552
	global_load_lds_dwordx4 v[214:215], off
	s_add_i32 m0, s68, 0x2000
	s_add_u32 s68, s30, 0x100000
	v_lshl_add_u64 v[216:217], s[30:31], 0, v[134:135]
	s_addc_u32 s69, s31, 0
	s_add_i32 s70, s57, s46
	global_load_lds_dwordx4 v[216:217], off
	v_lshl_add_u64 v[218:219], s[68:69], 0, v[130:131]
	s_mov_b32 m0, s70
	v_lshl_add_u64 v[220:221], s[36:37], 0, v[132:133]
	global_load_lds_dwordx4 v[218:219], off
	v_lshl_add_u64 v[218:219], s[68:69], 0, v[134:135]
	s_add_i32 m0, s70, 0x2000
	s_nop 0
	global_load_lds_dwordx4 v[218:219], off
	v_lshl_add_u64 v[218:219], s[36:37], 0, v[128:129]
	s_mov_b32 m0, s27
	s_nop 0
	global_load_lds_dwordx4 v[218:219], off
	s_mov_b32 m0, s47
	s_nop 0
	global_load_lds_dwordx4 v[220:221], off
	s_waitcnt vmcnt(8)
	s_waitcnt lgkmcnt(0)
	s_barrier
	s_setprio 1
	s_waitcnt lgkmcnt(0)
	v_mfma_f32_16x16x32_bf16 v[60:63], v[144:147], v[182:185], 0
	v_mfma_f32_16x16x32_bf16 v[56:59], v[158:161], v[182:185], 0
	v_mfma_f32_16x16x32_bf16 v[48:51], v[144:147], v[190:193], 0
	v_mfma_f32_16x16x32_bf16 v[40:43], v[158:161], v[190:193], 0
	v_mfma_f32_16x16x32_bf16 v[32:35], v[144:147], v[198:201], 0
	v_mfma_f32_16x16x32_bf16 v[24:27], v[158:161], v[198:201], 0
	v_mfma_f32_16x16x32_bf16 v[16:19], v[144:147], v[206:209], 0
	v_mfma_f32_16x16x32_bf16 v[8:11], v[158:161], v[206:209], 0
	v_mfma_f32_16x16x32_bf16 v[60:63], v[154:157], v[186:189], v[60:63]
	v_mfma_f32_16x16x32_bf16 v[56:59], v[162:165], v[186:189], v[56:59]
	v_mfma_f32_16x16x32_bf16 v[48:51], v[154:157], v[194:197], v[48:51]
	v_mfma_f32_16x16x32_bf16 v[40:43], v[162:165], v[194:197], v[40:43]
	v_mfma_f32_16x16x32_bf16 v[32:35], v[154:157], v[202:205], v[32:35]
	v_mfma_f32_16x16x32_bf16 v[24:27], v[162:165], v[202:205], v[24:27]
	v_mfma_f32_16x16x32_bf16 v[16:19], v[154:157], v[210:213], v[16:19]
	v_mfma_f32_16x16x32_bf16 v[8:11], v[162:165], v[210:213], v[8:11]
	s_setprio 0
	s_setprio 1
	v_mfma_f32_16x16x32_bf16 v[52:55], v[166:169], v[182:185], 0
	v_mfma_f32_16x16x32_bf16 v[44:47], v[174:177], v[182:185], 0
	v_mfma_f32_16x16x32_bf16 v[36:39], v[166:169], v[190:193], 0
	v_mfma_f32_16x16x32_bf16 v[28:31], v[174:177], v[190:193], 0
	v_mfma_f32_16x16x32_bf16 v[20:23], v[166:169], v[198:201], 0
	v_mfma_f32_16x16x32_bf16 v[12:15], v[174:177], v[198:201], 0
	v_mfma_f32_16x16x32_bf16 v[4:7], v[166:169], v[206:209], 0
	v_mfma_f32_16x16x32_bf16 v[0:3], v[174:177], v[206:209], 0
	v_mfma_f32_16x16x32_bf16 v[52:55], v[170:173], v[186:189], v[52:55]
	v_mfma_f32_16x16x32_bf16 v[44:47], v[178:181], v[186:189], v[44:47]
	v_mfma_f32_16x16x32_bf16 v[36:39], v[170:173], v[194:197], v[36:39]
	v_mfma_f32_16x16x32_bf16 v[28:31], v[178:181], v[194:197], v[28:31]
	v_mfma_f32_16x16x32_bf16 v[20:23], v[170:173], v[202:205], v[20:23]
	v_mfma_f32_16x16x32_bf16 v[12:15], v[178:181], v[202:205], v[12:15]
	v_mfma_f32_16x16x32_bf16 v[4:7], v[170:173], v[210:213], v[4:7]
	v_mfma_f32_16x16x32_bf16 v[0:3], v[178:181], v[210:213], v[0:3]
	s_setprio 0
	s_barrier
	s_add_i32 s68, 0, 0x18000
	v_add_u32_e32 v153, s68, v148
	s_add_i32 s69, 0, 0x1c000
	ds_read_b128 v[144:147], v153
	ds_read_b128 v[154:157], v153 offset:1024
	ds_read_b128 v[158:161], v153 offset:2048
	ds_read_b128 v[162:165], v153 offset:3072
	v_add_u32_e32 v153, s69, v148
	ds_read_b128 v[166:169], v153
	ds_read_b128 v[170:173], v153 offset:1024
	ds_read_b128 v[174:177], v153 offset:2048
	ds_read_b128 v[178:181], v153 offset:3072
	s_add_u32 s36, s36, 0x100000
	s_addc_u32 s37, s37, 0
	s_mov_b32 m0, s48
	v_lshl_add_u64 v[222:223], s[36:37], 0, v[128:129]
	ds_read_b128 v[182:185], v151 offset:32768
	ds_read_b128 v[186:189], v151 offset:33792
	ds_read_b128 v[190:193], v151 offset:34816
	ds_read_b128 v[194:197], v151 offset:35840
	ds_read_b128 v[198:201], v151 offset:36864
	ds_read_b128 v[202:205], v151 offset:37888
	ds_read_b128 v[206:209], v151 offset:38912
	ds_read_b128 v[210:213], v151 offset:39936
	global_load_lds_dwordx4 v[222:223], off
	v_lshl_add_u64 v[222:223], s[36:37], 0, v[132:133]
	s_mov_b32 m0, s49
	s_nop 0
	global_load_lds_dwordx4 v[222:223], off
	s_waitcnt vmcnt(8)
	s_waitcnt lgkmcnt(0)
	s_barrier
	s_setprio 1
	s_waitcnt lgkmcnt(0)
	v_mfma_f32_16x16x32_bf16 v[124:127], v[144:147], v[182:185], v[124:127]
	v_mfma_f32_16x16x32_bf16 v[120:123], v[158:161], v[182:185], v[120:123]
	v_mfma_f32_16x16x32_bf16 v[112:115], v[144:147], v[190:193], v[112:115]
	v_mfma_f32_16x16x32_bf16 v[104:107], v[158:161], v[190:193], v[104:107]
	v_mfma_f32_16x16x32_bf16 v[96:99], v[144:147], v[198:201], v[96:99]
	v_mfma_f32_16x16x32_bf16 v[88:91], v[158:161], v[198:201], v[88:91]
	v_mfma_f32_16x16x32_bf16 v[80:83], v[144:147], v[206:209], v[80:83]
	v_mfma_f32_16x16x32_bf16 v[72:75], v[158:161], v[206:209], v[72:75]
	v_mfma_f32_16x16x32_bf16 v[124:127], v[154:157], v[186:189], v[124:127]
	v_mfma_f32_16x16x32_bf16 v[120:123], v[162:165], v[186:189], v[120:123]
	v_mfma_f32_16x16x32_bf16 v[112:115], v[154:157], v[194:197], v[112:115]
	v_mfma_f32_16x16x32_bf16 v[104:107], v[162:165], v[194:197], v[104:107]
	v_mfma_f32_16x16x32_bf16 v[96:99], v[154:157], v[202:205], v[96:99]
	v_mfma_f32_16x16x32_bf16 v[88:91], v[162:165], v[202:205], v[88:91]
	v_mfma_f32_16x16x32_bf16 v[80:83], v[154:157], v[210:213], v[80:83]
	v_mfma_f32_16x16x32_bf16 v[72:75], v[162:165], v[210:213], v[72:75]
	s_setprio 0
	s_setprio 1
	v_mfma_f32_16x16x32_bf16 v[116:119], v[166:169], v[182:185], v[116:119]
	v_mfma_f32_16x16x32_bf16 v[108:111], v[174:177], v[182:185], v[108:111]
	v_mfma_f32_16x16x32_bf16 v[100:103], v[166:169], v[190:193], v[100:103]
	v_mfma_f32_16x16x32_bf16 v[92:95], v[174:177], v[190:193], v[92:95]
	v_mfma_f32_16x16x32_bf16 v[84:87], v[166:169], v[198:201], v[84:87]
	v_mfma_f32_16x16x32_bf16 v[76:79], v[174:177], v[198:201], v[76:79]
	v_mfma_f32_16x16x32_bf16 v[68:71], v[166:169], v[206:209], v[68:71]
	v_mfma_f32_16x16x32_bf16 v[64:67], v[174:177], v[206:209], v[64:67]
	v_mfma_f32_16x16x32_bf16 v[116:119], v[170:173], v[186:189], v[116:119]
	v_mfma_f32_16x16x32_bf16 v[108:111], v[178:181], v[186:189], v[108:111]
	v_mfma_f32_16x16x32_bf16 v[100:103], v[170:173], v[194:197], v[100:103]
	v_mfma_f32_16x16x32_bf16 v[92:95], v[178:181], v[194:197], v[92:95]
	v_mfma_f32_16x16x32_bf16 v[84:87], v[170:173], v[202:205], v[84:87]
	v_mfma_f32_16x16x32_bf16 v[76:79], v[178:181], v[202:205], v[76:79]
	v_mfma_f32_16x16x32_bf16 v[68:71], v[170:173], v[210:213], v[68:71]
	v_mfma_f32_16x16x32_bf16 v[64:67], v[178:181], v[210:213], v[64:67]
	s_setprio 0
	s_barrier
	s_add_i32 s36, s68, s46
	v_lshl_add_u64 v[214:215], v[214:215], 0, s[14:15]
	s_mov_b32 m0, s36
	ds_read_b128 v[182:185], v151 offset:49152
	ds_read_b128 v[186:189], v151 offset:50176
	ds_read_b128 v[190:193], v151 offset:51200
	ds_read_b128 v[194:197], v151 offset:52224
	ds_read_b128 v[198:201], v151 offset:53248
	ds_read_b128 v[202:205], v151 offset:54272
	ds_read_b128 v[206:209], v151 offset:55296
	ds_read_b128 v[210:213], v151 offset:56320
	global_load_lds_dwordx4 v[214:215], off
	s_add_i32 m0, s36, 0x2000
	s_add_u32 s30, s30, 0x100080
	v_lshl_add_u64 v[214:215], v[216:217], 0, s[14:15]
	s_addc_u32 s31, s31, 0
	s_add_i32 s36, s69, s46
	global_load_lds_dwordx4 v[214:215], off
	v_lshl_add_u64 v[214:215], s[30:31], 0, v[130:131]
	s_mov_b32 m0, s36
	s_nop 0
	global_load_lds_dwordx4 v[214:215], off
	v_lshl_add_u64 v[214:215], s[30:31], 0, v[134:135]
	s_add_i32 m0, s36, 0x2000
	s_nop 0
	global_load_lds_dwordx4 v[214:215], off
	v_lshl_add_u64 v[214:215], v[218:219], 0, s[14:15]
	s_mov_b32 m0, s53
	s_nop 0
	global_load_lds_dwordx4 v[214:215], off
	v_lshl_add_u64 v[214:215], v[220:221], 0, s[14:15]
	s_mov_b32 m0, s54
	s_nop 0
	global_load_lds_dwordx4 v[214:215], off
	s_waitcnt vmcnt(8)
	s_waitcnt lgkmcnt(0)
	s_barrier
	s_setprio 1
	s_waitcnt lgkmcnt(0)
	v_mfma_f32_16x16x32_bf16 v[60:63], v[144:147], v[182:185], v[60:63]
	v_mfma_f32_16x16x32_bf16 v[56:59], v[158:161], v[182:185], v[56:59]
	v_mfma_f32_16x16x32_bf16 v[48:51], v[144:147], v[190:193], v[48:51]
	v_mfma_f32_16x16x32_bf16 v[40:43], v[158:161], v[190:193], v[40:43]
	v_mfma_f32_16x16x32_bf16 v[32:35], v[144:147], v[198:201], v[32:35]
	v_mfma_f32_16x16x32_bf16 v[24:27], v[158:161], v[198:201], v[24:27]
	v_mfma_f32_16x16x32_bf16 v[16:19], v[144:147], v[206:209], v[16:19]
	v_mfma_f32_16x16x32_bf16 v[8:11], v[158:161], v[206:209], v[8:11]
	v_mfma_f32_16x16x32_bf16 v[60:63], v[154:157], v[186:189], v[60:63]
	v_mfma_f32_16x16x32_bf16 v[56:59], v[162:165], v[186:189], v[56:59]
	v_mfma_f32_16x16x32_bf16 v[48:51], v[154:157], v[194:197], v[48:51]
	v_mfma_f32_16x16x32_bf16 v[40:43], v[162:165], v[194:197], v[40:43]
	v_mfma_f32_16x16x32_bf16 v[32:35], v[154:157], v[202:205], v[32:35]
	v_mfma_f32_16x16x32_bf16 v[24:27], v[162:165], v[202:205], v[24:27]
	v_mfma_f32_16x16x32_bf16 v[16:19], v[154:157], v[210:213], v[16:19]
	v_mfma_f32_16x16x32_bf16 v[8:11], v[162:165], v[210:213], v[8:11]
	s_setprio 0
	s_setprio 1
	v_mfma_f32_16x16x32_bf16 v[52:55], v[166:169], v[182:185], v[52:55]
	v_mfma_f32_16x16x32_bf16 v[44:47], v[174:177], v[182:185], v[44:47]
	v_mfma_f32_16x16x32_bf16 v[36:39], v[166:169], v[190:193], v[36:39]
	v_mfma_f32_16x16x32_bf16 v[28:31], v[174:177], v[190:193], v[28:31]
	v_mfma_f32_16x16x32_bf16 v[20:23], v[166:169], v[198:201], v[20:23]
	v_mfma_f32_16x16x32_bf16 v[12:15], v[174:177], v[198:201], v[12:15]
	v_mfma_f32_16x16x32_bf16 v[4:7], v[166:169], v[206:209], v[4:7]
	v_mfma_f32_16x16x32_bf16 v[0:3], v[174:177], v[206:209], v[0:3]
	v_mfma_f32_16x16x32_bf16 v[52:55], v[170:173], v[186:189], v[52:55]
	v_mfma_f32_16x16x32_bf16 v[44:47], v[178:181], v[186:189], v[44:47]
	v_mfma_f32_16x16x32_bf16 v[36:39], v[170:173], v[194:197], v[36:39]
	v_mfma_f32_16x16x32_bf16 v[28:31], v[178:181], v[194:197], v[28:31]
	v_mfma_f32_16x16x32_bf16 v[20:23], v[170:173], v[202:205], v[20:23]
	v_mfma_f32_16x16x32_bf16 v[12:15], v[178:181], v[202:205], v[12:15]
	v_mfma_f32_16x16x32_bf16 v[4:7], v[170:173], v[210:213], v[4:7]
	v_mfma_f32_16x16x32_bf16 v[0:3], v[178:181], v[210:213], v[0:3]
	s_setprio 0
	s_barrier
	s_add_i32 s67, s67, 2
	s_add_u32 s28, s28, 0x100
	s_addc_u32 s29, s29, 0
	s_add_u32 s61, s61, 0x100
	s_addc_u32 s62, s62, 0
	s_cmp_gt_u32 s67, 61
	s_cbranch_scc1 .Lpost_p1

.Lpost_p1:
	s_and_b64 vcc, exec, s[16:17]
	s_cbranch_vccz .LBB0_232
	s_barrier

.LBB0_632:
	s_ashr_i32 s29, s28, 31
	s_lshl_b64 s[30:31], s[28:29], 20
	s_add_u32 s30, s2, s30
	s_addc_u32 s31, s25, s31
	s_and_b64 s[36:37], s[4:5], exec
	s_cselect_b32 s29, s31, s39
	s_cselect_b32 s71, s30, s38
	s_ashr_i32 s27, s26, 31
	s_lshl_b64 s[36:37], s[26:27], 20
	s_add_u32 s36, s34, s36
	s_addc_u32 s37, s35, s37
	s_and_b64 s[50:51], s[4:5], exec
	s_cselect_b32 s72, s37, s49
	s_cselect_b32 s73, s36, s48
	s_lshl_b32 s27, s46, 8
	s_add_i32 s27, s27, s58
	s_add_u32 s74, s48, 0x100
	v_lshl_add_u64 v[144:145], s[38:39], 0, v[136:137]
	v_lshl_add_u64 v[146:147], s[38:39], 0, v[138:139]
	s_addc_u32 s75, s49, 0
	s_mov_b32 s76, -2
	s_mov_b64 s[46:47], 0
	v_add_u32_e32 v160, s68, v164
	v_add_u32_e32 v178, s69, v164
	s_add_u32 s48, s38, s46
	ds_read_b128 v[148:151], v160
	ds_read_b128 v[152:155], v160 offset:1024
	ds_read_b128 v[156:159], v160 offset:2048
	ds_read_b128 v[160:163], v160 offset:3072
	ds_read_b128 v[166:169], v178
	ds_read_b128 v[170:173], v178 offset:1024
	ds_read_b128 v[174:177], v178 offset:2048
	ds_read_b128 v[178:181], v178 offset:3072
	s_addc_u32 s49, s39, s47
	s_add_u32 s48, s48, 0x100
	s_addc_u32 s49, s49, 0
	s_add_u32 s67, s74, s46
	s_addc_u32 s77, s75, s47
	s_cmpk_eq_i32 s46, 0xf00
	s_cselect_b32 s51, s29, s49
	s_cselect_b32 s50, s71, s48
	s_cselect_b32 s49, s72, s77
	s_cselect_b32 s48, s73, s67
	v_lshl_add_u64 v[214:215], v[144:145], 0, s[46:47]
	s_add_i32 m0, s54, 0xc000
	ds_read_b128 v[182:185], v165
	ds_read_b128 v[186:189], v165 offset:1024
	ds_read_b128 v[190:193], v165 offset:2048
	ds_read_b128 v[194:197], v165 offset:3072
	ds_read_b128 v[198:201], v165 offset:4096
	ds_read_b128 v[202:205], v165 offset:5120
	ds_read_b128 v[206:209], v165 offset:6144
	ds_read_b128 v[210:213], v165 offset:7168
	global_load_lds_dwordx4 v[214:215], off
	v_lshl_add_u64 v[214:215], v[146:147], 0, s[46:47]
	s_add_i32 m0, s54, 0xe000
	s_nop 0
	global_load_lds_dwordx4 v[214:215], off
	s_waitcnt vmcnt(8)
	s_waitcnt lgkmcnt(0)
	s_barrier
	s_setprio 1
	s_waitcnt lgkmcnt(0)
	v_mfma_i32_16x16x64_i8 v[124:127], v[148:151], v[182:185], 0
	v_mfma_i32_16x16x64_i8 v[120:123], v[156:159], v[182:185], 0
	v_mfma_i32_16x16x64_i8 v[108:111], v[148:151], v[190:193], 0
	v_mfma_i32_16x16x64_i8 v[104:107], v[156:159], v[190:193], 0
	v_mfma_i32_16x16x64_i8 v[92:95], v[148:151], v[198:201], 0
	v_mfma_i32_16x16x64_i8 v[88:91], v[156:159], v[198:201], 0
	v_mfma_i32_16x16x64_i8 v[76:79], v[148:151], v[206:209], 0
	v_mfma_i32_16x16x64_i8 v[72:75], v[156:159], v[206:209], 0
	v_mfma_i32_16x16x64_i8 v[124:127], v[152:155], v[186:189], v[124:127]
	v_mfma_i32_16x16x64_i8 v[120:123], v[160:163], v[186:189], v[120:123]
	v_mfma_i32_16x16x64_i8 v[108:111], v[152:155], v[194:197], v[108:111]
	v_mfma_i32_16x16x64_i8 v[104:107], v[160:163], v[194:197], v[104:107]
	v_mfma_i32_16x16x64_i8 v[92:95], v[152:155], v[202:205], v[92:95]
	v_mfma_i32_16x16x64_i8 v[88:91], v[160:163], v[202:205], v[88:91]
	v_mfma_i32_16x16x64_i8 v[76:79], v[152:155], v[210:213], v[76:79]
	v_mfma_i32_16x16x64_i8 v[72:75], v[160:163], v[210:213], v[72:75]
	s_setprio 0
	s_setprio 1
	v_mfma_i32_16x16x64_i8 v[116:119], v[166:169], v[182:185], 0
	v_mfma_i32_16x16x64_i8 v[112:115], v[174:177], v[182:185], 0
	v_mfma_i32_16x16x64_i8 v[100:103], v[166:169], v[190:193], 0
	v_mfma_i32_16x16x64_i8 v[96:99], v[174:177], v[190:193], 0
	v_mfma_i32_16x16x64_i8 v[84:87], v[166:169], v[198:201], 0
	v_mfma_i32_16x16x64_i8 v[80:83], v[174:177], v[198:201], 0
	v_mfma_i32_16x16x64_i8 v[68:71], v[166:169], v[206:209], 0
	v_mfma_i32_16x16x64_i8 v[64:67], v[174:177], v[206:209], 0
	v_mfma_i32_16x16x64_i8 v[116:119], v[170:173], v[186:189], v[116:119]
	v_mfma_i32_16x16x64_i8 v[112:115], v[178:181], v[186:189], v[112:115]
	v_mfma_i32_16x16x64_i8 v[100:103], v[170:173], v[194:197], v[100:103]
	v_mfma_i32_16x16x64_i8 v[96:99], v[178:181], v[194:197], v[96:99]
	v_mfma_i32_16x16x64_i8 v[84:87], v[170:173], v[202:205], v[84:87]
	v_mfma_i32_16x16x64_i8 v[80:83], v[178:181], v[202:205], v[80:83]
	v_mfma_i32_16x16x64_i8 v[68:71], v[170:173], v[210:213], v[68:71]
	v_mfma_i32_16x16x64_i8 v[64:67], v[178:181], v[210:213], v[64:67]
	s_setprio 0
	s_barrier
	s_add_i32 s67, s68, s45
	v_lshl_add_u64 v[214:215], s[48:49], 0, v[132:133]
	s_mov_b32 m0, s67
	ds_read_b128 v[182:185], v165 offset:16384
	ds_read_b128 v[186:189], v165 offset:17408
	ds_read_b128 v[190:193], v165 offset:18432
	ds_read_b128 v[194:197], v165 offset:19456
	ds_read_b128 v[198:201], v165 offset:20480
	ds_read_b128 v[202:205], v165 offset:21504
	ds_read_b128 v[206:209], v165 offset:22528
	ds_read_b128 v[210:213], v165 offset:23552
	global_load_lds_dwordx4 v[214:215], off
	s_add_i32 m0, s67, 0x2000
	s_add_u32 s78, s48, 0x80000
	v_lshl_add_u64 v[216:217], s[48:49], 0, v[128:129]
	s_addc_u32 s79, s49, 0
	s_add_i32 s67, s69, s45
	global_load_lds_dwordx4 v[216:217], off
	v_lshl_add_u64 v[218:219], s[78:79], 0, v[132:133]
	s_mov_b32 m0, s67
	v_lshl_add_u64 v[220:221], s[50:51], 0, v[130:131]
	global_load_lds_dwordx4 v[218:219], off
	v_lshl_add_u64 v[218:219], s[78:79], 0, v[128:129]
	s_add_i32 m0, s67, 0x2000
	s_nop 0
	global_load_lds_dwordx4 v[218:219], off
	v_lshl_add_u64 v[218:219], s[50:51], 0, v[134:135]
	s_mov_b32 m0, s54
	s_nop 0
	global_load_lds_dwordx4 v[218:219], off
	s_mov_b32 m0, s55
	s_nop 0
	global_load_lds_dwordx4 v[220:221], off
	s_waitcnt vmcnt(8)
	s_waitcnt lgkmcnt(0)
	s_barrier
	s_setprio 1
	s_waitcnt lgkmcnt(0)
	v_mfma_i32_16x16x64_i8 v[60:63], v[148:151], v[182:185], 0
	v_mfma_i32_16x16x64_i8 v[56:59], v[156:159], v[182:185], 0
	v_mfma_i32_16x16x64_i8 v[44:47], v[148:151], v[190:193], 0
	v_mfma_i32_16x16x64_i8 v[40:43], v[156:159], v[190:193], 0
	v_mfma_i32_16x16x64_i8 v[28:31], v[148:151], v[198:201], 0
	v_mfma_i32_16x16x64_i8 v[24:27], v[156:159], v[198:201], 0
	v_mfma_i32_16x16x64_i8 v[12:15], v[148:151], v[206:209], 0
	v_mfma_i32_16x16x64_i8 v[8:11], v[156:159], v[206:209], 0
	v_mfma_i32_16x16x64_i8 v[60:63], v[152:155], v[186:189], v[60:63]
	v_mfma_i32_16x16x64_i8 v[56:59], v[160:163], v[186:189], v[56:59]
	v_mfma_i32_16x16x64_i8 v[44:47], v[152:155], v[194:197], v[44:47]
	v_mfma_i32_16x16x64_i8 v[40:43], v[160:163], v[194:197], v[40:43]
	v_mfma_i32_16x16x64_i8 v[28:31], v[152:155], v[202:205], v[28:31]
	v_mfma_i32_16x16x64_i8 v[24:27], v[160:163], v[202:205], v[24:27]
	v_mfma_i32_16x16x64_i8 v[12:15], v[152:155], v[210:213], v[12:15]
	v_mfma_i32_16x16x64_i8 v[8:11], v[160:163], v[210:213], v[8:11]
	s_setprio 0
	s_setprio 1
	v_mfma_i32_16x16x64_i8 v[52:55], v[166:169], v[182:185], 0
	v_mfma_i32_16x16x64_i8 v[48:51], v[174:177], v[182:185], 0
	v_mfma_i32_16x16x64_i8 v[36:39], v[166:169], v[190:193], 0
	v_mfma_i32_16x16x64_i8 v[32:35], v[174:177], v[190:193], 0
	v_mfma_i32_16x16x64_i8 v[20:23], v[166:169], v[198:201], 0
	v_mfma_i32_16x16x64_i8 v[16:19], v[174:177], v[198:201], 0
	v_mfma_i32_16x16x64_i8 v[4:7], v[166:169], v[206:209], 0
	v_mfma_i32_16x16x64_i8 v[0:3], v[174:177], v[206:209], 0
	v_mfma_i32_16x16x64_i8 v[52:55], v[170:173], v[186:189], v[52:55]
	v_mfma_i32_16x16x64_i8 v[48:51], v[178:181], v[186:189], v[48:51]
	v_mfma_i32_16x16x64_i8 v[36:39], v[170:173], v[194:197], v[36:39]
	v_mfma_i32_16x16x64_i8 v[32:35], v[178:181], v[194:197], v[32:35]
	v_mfma_i32_16x16x64_i8 v[20:23], v[170:173], v[202:205], v[20:23]
	v_mfma_i32_16x16x64_i8 v[16:19], v[178:181], v[202:205], v[16:19]
	v_mfma_i32_16x16x64_i8 v[4:7], v[170:173], v[210:213], v[4:7]
	v_mfma_i32_16x16x64_i8 v[0:3], v[178:181], v[210:213], v[0:3]
	s_setprio 0
	s_barrier
	s_add_i32 s67, 0, 0x18000
	s_add_i32 s77, 0, 0x1c000
	v_add_u32_e32 v160, s67, v164
	v_add_u32_e32 v178, s77, v164
	ds_read_b128 v[148:151], v160
	ds_read_b128 v[152:155], v160 offset:1024
	ds_read_b128 v[156:159], v160 offset:2048
	ds_read_b128 v[160:163], v160 offset:3072
	ds_read_b128 v[166:169], v178
	ds_read_b128 v[170:173], v178 offset:1024
	ds_read_b128 v[174:177], v178 offset:2048
	ds_read_b128 v[178:181], v178 offset:3072
	s_add_u32 s50, s50, 0x80000
	s_addc_u32 s51, s51, 0
	s_mov_b32 m0, s56
	v_lshl_add_u64 v[222:223], s[50:51], 0, v[134:135]
	ds_read_b128 v[182:185], v165 offset:32768
	ds_read_b128 v[186:189], v165 offset:33792
	ds_read_b128 v[190:193], v165 offset:34816
	ds_read_b128 v[194:197], v165 offset:35840
	ds_read_b128 v[198:201], v165 offset:36864
	ds_read_b128 v[202:205], v165 offset:37888
	ds_read_b128 v[206:209], v165 offset:38912
	ds_read_b128 v[210:213], v165 offset:39936
	global_load_lds_dwordx4 v[222:223], off
	v_lshl_add_u64 v[222:223], s[50:51], 0, v[130:131]
	s_mov_b32 m0, s57
	s_nop 0
	global_load_lds_dwordx4 v[222:223], off
	s_waitcnt vmcnt(8)
	s_waitcnt lgkmcnt(0)
	s_barrier
	s_setprio 1
	s_waitcnt lgkmcnt(0)
	v_mfma_i32_16x16x64_i8 v[124:127], v[148:151], v[182:185], v[124:127]
	v_mfma_i32_16x16x64_i8 v[120:123], v[156:159], v[182:185], v[120:123]
	v_mfma_i32_16x16x64_i8 v[108:111], v[148:151], v[190:193], v[108:111]
	v_mfma_i32_16x16x64_i8 v[104:107], v[156:159], v[190:193], v[104:107]
	v_mfma_i32_16x16x64_i8 v[92:95], v[148:151], v[198:201], v[92:95]
	v_mfma_i32_16x16x64_i8 v[88:91], v[156:159], v[198:201], v[88:91]
	v_mfma_i32_16x16x64_i8 v[76:79], v[148:151], v[206:209], v[76:79]
	v_mfma_i32_16x16x64_i8 v[72:75], v[156:159], v[206:209], v[72:75]
	v_mfma_i32_16x16x64_i8 v[124:127], v[152:155], v[186:189], v[124:127]
	v_mfma_i32_16x16x64_i8 v[120:123], v[160:163], v[186:189], v[120:123]
	v_mfma_i32_16x16x64_i8 v[108:111], v[152:155], v[194:197], v[108:111]
	v_mfma_i32_16x16x64_i8 v[104:107], v[160:163], v[194:197], v[104:107]
	v_mfma_i32_16x16x64_i8 v[92:95], v[152:155], v[202:205], v[92:95]
	v_mfma_i32_16x16x64_i8 v[88:91], v[160:163], v[202:205], v[88:91]
	v_mfma_i32_16x16x64_i8 v[76:79], v[152:155], v[210:213], v[76:79]
	v_mfma_i32_16x16x64_i8 v[72:75], v[160:163], v[210:213], v[72:75]
	s_setprio 0
	s_setprio 1
	v_mfma_i32_16x16x64_i8 v[116:119], v[166:169], v[182:185], v[116:119]
	v_mfma_i32_16x16x64_i8 v[112:115], v[174:177], v[182:185], v[112:115]
	v_mfma_i32_16x16x64_i8 v[100:103], v[166:169], v[190:193], v[100:103]
	v_mfma_i32_16x16x64_i8 v[96:99], v[174:177], v[190:193], v[96:99]
	v_mfma_i32_16x16x64_i8 v[84:87], v[166:169], v[198:201], v[84:87]
	v_mfma_i32_16x16x64_i8 v[80:83], v[174:177], v[198:201], v[80:83]
	v_mfma_i32_16x16x64_i8 v[68:71], v[166:169], v[206:209], v[68:71]
	v_mfma_i32_16x16x64_i8 v[64:67], v[174:177], v[206:209], v[64:67]
	v_mfma_i32_16x16x64_i8 v[116:119], v[170:173], v[186:189], v[116:119]
	v_mfma_i32_16x16x64_i8 v[112:115], v[178:181], v[186:189], v[112:115]
	v_mfma_i32_16x16x64_i8 v[100:103], v[170:173], v[194:197], v[100:103]
	v_mfma_i32_16x16x64_i8 v[96:99], v[178:181], v[194:197], v[96:99]
	v_mfma_i32_16x16x64_i8 v[84:87], v[170:173], v[202:205], v[84:87]
	v_mfma_i32_16x16x64_i8 v[80:83], v[178:181], v[202:205], v[80:83]
	v_mfma_i32_16x16x64_i8 v[68:71], v[170:173], v[210:213], v[68:71]
	v_mfma_i32_16x16x64_i8 v[64:67], v[178:181], v[210:213], v[64:67]
	s_setprio 0
	s_barrier
	s_add_i32 s50, s67, s45
	v_lshl_add_u64 v[214:215], v[214:215], 0, s[18:19]
	s_mov_b32 m0, s50
	ds_read_b128 v[182:185], v165 offset:49152
	ds_read_b128 v[186:189], v165 offset:50176
	ds_read_b128 v[190:193], v165 offset:51200
	ds_read_b128 v[194:197], v165 offset:52224
	ds_read_b128 v[198:201], v165 offset:53248
	ds_read_b128 v[202:205], v165 offset:54272
	ds_read_b128 v[206:209], v165 offset:55296
	ds_read_b128 v[210:213], v165 offset:56320
	global_load_lds_dwordx4 v[214:215], off
	s_add_i32 m0, s50, 0x2000
	s_add_u32 s48, s48, 0x80080
	v_lshl_add_u64 v[214:215], v[216:217], 0, s[18:19]
	s_addc_u32 s49, s49, 0
	s_add_i32 s50, s77, s45
	global_load_lds_dwordx4 v[214:215], off
	v_lshl_add_u64 v[214:215], s[48:49], 0, v[132:133]
	s_mov_b32 m0, s50
	s_nop 0
	global_load_lds_dwordx4 v[214:215], off
	v_lshl_add_u64 v[214:215], s[48:49], 0, v[128:129]
	s_add_i32 m0, s50, 0x2000
	s_nop 0
	global_load_lds_dwordx4 v[214:215], off
	v_lshl_add_u64 v[214:215], v[218:219], 0, s[18:19]
	s_mov_b32 m0, s60
	s_nop 0
	global_load_lds_dwordx4 v[214:215], off
	v_lshl_add_u64 v[214:215], v[220:221], 0, s[18:19]
	s_mov_b32 m0, s61
	s_nop 0
	global_load_lds_dwordx4 v[214:215], off
	s_waitcnt vmcnt(8)
	s_waitcnt lgkmcnt(0)
	s_barrier
	s_setprio 1
	s_waitcnt lgkmcnt(0)
	v_mfma_i32_16x16x64_i8 v[60:63], v[148:151], v[182:185], v[60:63]
	v_mfma_i32_16x16x64_i8 v[56:59], v[156:159], v[182:185], v[56:59]
	v_mfma_i32_16x16x64_i8 v[44:47], v[148:151], v[190:193], v[44:47]
	v_mfma_i32_16x16x64_i8 v[40:43], v[156:159], v[190:193], v[40:43]
	v_mfma_i32_16x16x64_i8 v[28:31], v[148:151], v[198:201], v[28:31]
	v_mfma_i32_16x16x64_i8 v[24:27], v[156:159], v[198:201], v[24:27]
	v_mfma_i32_16x16x64_i8 v[12:15], v[148:151], v[206:209], v[12:15]
	v_mfma_i32_16x16x64_i8 v[8:11], v[156:159], v[206:209], v[8:11]
	v_mfma_i32_16x16x64_i8 v[60:63], v[152:155], v[186:189], v[60:63]
	v_mfma_i32_16x16x64_i8 v[56:59], v[160:163], v[186:189], v[56:59]
	v_mfma_i32_16x16x64_i8 v[44:47], v[152:155], v[194:197], v[44:47]
	v_mfma_i32_16x16x64_i8 v[40:43], v[160:163], v[194:197], v[40:43]
	v_mfma_i32_16x16x64_i8 v[28:31], v[152:155], v[202:205], v[28:31]
	v_mfma_i32_16x16x64_i8 v[24:27], v[160:163], v[202:205], v[24:27]
	v_mfma_i32_16x16x64_i8 v[12:15], v[152:155], v[210:213], v[12:15]
	v_mfma_i32_16x16x64_i8 v[8:11], v[160:163], v[210:213], v[8:11]
	s_setprio 0
	s_setprio 1
	v_mfma_i32_16x16x64_i8 v[52:55], v[166:169], v[182:185], v[52:55]
	v_mfma_i32_16x16x64_i8 v[48:51], v[174:177], v[182:185], v[48:51]
	v_mfma_i32_16x16x64_i8 v[36:39], v[166:169], v[190:193], v[36:39]
	v_mfma_i32_16x16x64_i8 v[32:35], v[174:177], v[190:193], v[32:35]
	v_mfma_i32_16x16x64_i8 v[20:23], v[166:169], v[198:201], v[20:23]
	v_mfma_i32_16x16x64_i8 v[16:19], v[174:177], v[198:201], v[16:19]
	v_mfma_i32_16x16x64_i8 v[4:7], v[166:169], v[206:209], v[4:7]
	v_mfma_i32_16x16x64_i8 v[0:3], v[174:177], v[206:209], v[0:3]
	v_mfma_i32_16x16x64_i8 v[52:55], v[170:173], v[186:189], v[52:55]
	v_mfma_i32_16x16x64_i8 v[48:51], v[178:181], v[186:189], v[48:51]
	v_mfma_i32_16x16x64_i8 v[36:39], v[170:173], v[194:197], v[36:39]
	v_mfma_i32_16x16x64_i8 v[32:35], v[178:181], v[194:197], v[32:35]
	v_mfma_i32_16x16x64_i8 v[20:23], v[170:173], v[202:205], v[20:23]
	v_mfma_i32_16x16x64_i8 v[16:19], v[178:181], v[202:205], v[16:19]
	v_mfma_i32_16x16x64_i8 v[4:7], v[170:173], v[210:213], v[4:7]
	v_mfma_i32_16x16x64_i8 v[0:3], v[178:181], v[210:213], v[0:3]
	s_setprio 0
	s_barrier
	s_add_i32 s76, s76, 2
	s_add_u32 s46, s46, 0x100
	s_addc_u32 s47, s47, 0
	s_cmp_gt_u32 s76, 29
	s_cbranch_scc1 .LBB0_636
	s_branch .LBB0_634

.LBB0_770:
	s_ashr_i32 s47, s46, 31
	s_lshl_b64 s[48:49], s[46:47], 20
	s_add_u32 s48, s16, s48
	s_addc_u32 s49, s17, s49
	s_and_b64 s[50:51], s[6:7], exec
	s_cselect_b32 s47, s49, s55
	s_cselect_b32 s75, s48, s54
	s_ashr_i32 s39, s38, 31
	s_lshl_b64 s[50:51], s[38:39], 20
	s_add_u32 s50, s2, s50
	s_addc_u32 s51, s31, s51
	s_and_b64 s[58:59], s[6:7], exec
	s_cselect_b32 s39, s51, s57
	s_cselect_b32 s76, s50, s56
	s_add_u32 s54, s54, 0x80080
	s_addc_u32 s55, s55, 0
	s_add_u32 s77, s56, 0x100
	s_addc_u32 s78, s57, 0
	s_mov_b32 s79, -2
	ds_read_b128 v[144:147], v153
	ds_read_b128 v[148:151], v153 offset:1024
	ds_read_b128 v[156:159], v153 offset:2048
	ds_read_b128 v[160:163], v153 offset:3072
	ds_read_b128 v[164:167], v154
	ds_read_b128 v[168:171], v154 offset:1024
	ds_read_b128 v[172:175], v154 offset:2048
	ds_read_b128 v[176:179], v154 offset:3072
	s_add_u32 s56, s54, 0xfff80080
	s_addc_u32 s57, s55, -1
	s_cmp_eq_u32 s79, 28
	s_cselect_b32 s59, s47, s57
	s_cselect_b32 s58, s75, s56
	s_cselect_b32 s57, s39, s78
	s_cselect_b32 s56, s76, s77
	v_lshl_add_u64 v[212:213], s[54:55], 0, v[136:137]
	s_add_i32 m0, s37, 0xc000
	ds_read_b128 v[180:183], v155
	ds_read_b128 v[184:187], v155 offset:1024
	ds_read_b128 v[188:191], v155 offset:2048
	ds_read_b128 v[192:195], v155 offset:3072
	ds_read_b128 v[196:199], v155 offset:4096
	ds_read_b128 v[200:203], v155 offset:5120
	ds_read_b128 v[204:207], v155 offset:6144
	ds_read_b128 v[208:211], v155 offset:7168
	global_load_lds_dwordx4 v[212:213], off
	v_lshl_add_u64 v[212:213], s[54:55], 0, v[138:139]
	s_add_i32 m0, s37, 0xe000
	s_nop 0
	global_load_lds_dwordx4 v[212:213], off
	s_waitcnt vmcnt(8)
	s_waitcnt lgkmcnt(0)
	s_barrier
	s_setprio 1
	s_waitcnt lgkmcnt(0)
	v_mfma_i32_16x16x64_i8 v[124:127], v[144:147], v[180:183], 0
	v_mfma_i32_16x16x64_i8 v[120:123], v[156:159], v[180:183], 0
	v_mfma_i32_16x16x64_i8 v[108:111], v[144:147], v[188:191], 0
	v_mfma_i32_16x16x64_i8 v[104:107], v[156:159], v[188:191], 0
	v_mfma_i32_16x16x64_i8 v[92:95], v[144:147], v[196:199], 0
	v_mfma_i32_16x16x64_i8 v[88:91], v[156:159], v[196:199], 0
	v_mfma_i32_16x16x64_i8 v[76:79], v[144:147], v[204:207], 0
	v_mfma_i32_16x16x64_i8 v[72:75], v[156:159], v[204:207], 0
	v_mfma_i32_16x16x64_i8 v[124:127], v[148:151], v[184:187], v[124:127]
	v_mfma_i32_16x16x64_i8 v[120:123], v[160:163], v[184:187], v[120:123]
	v_mfma_i32_16x16x64_i8 v[108:111], v[148:151], v[192:195], v[108:111]
	v_mfma_i32_16x16x64_i8 v[104:107], v[160:163], v[192:195], v[104:107]
	v_mfma_i32_16x16x64_i8 v[92:95], v[148:151], v[200:203], v[92:95]
	v_mfma_i32_16x16x64_i8 v[88:91], v[160:163], v[200:203], v[88:91]
	v_mfma_i32_16x16x64_i8 v[76:79], v[148:151], v[208:211], v[76:79]
	v_mfma_i32_16x16x64_i8 v[72:75], v[160:163], v[208:211], v[72:75]
	s_setprio 0
	s_setprio 1
	v_mfma_i32_16x16x64_i8 v[116:119], v[164:167], v[180:183], 0
	v_mfma_i32_16x16x64_i8 v[112:115], v[172:175], v[180:183], 0
	v_mfma_i32_16x16x64_i8 v[100:103], v[164:167], v[188:191], 0
	v_mfma_i32_16x16x64_i8 v[96:99], v[172:175], v[188:191], 0
	v_mfma_i32_16x16x64_i8 v[84:87], v[164:167], v[196:199], 0
	v_mfma_i32_16x16x64_i8 v[80:83], v[172:175], v[196:199], 0
	v_mfma_i32_16x16x64_i8 v[68:71], v[164:167], v[204:207], 0
	v_mfma_i32_16x16x64_i8 v[64:67], v[172:175], v[204:207], 0
	v_mfma_i32_16x16x64_i8 v[116:119], v[168:171], v[184:187], v[116:119]
	v_mfma_i32_16x16x64_i8 v[112:115], v[176:179], v[184:187], v[112:115]
	v_mfma_i32_16x16x64_i8 v[100:103], v[168:171], v[192:195], v[100:103]
	v_mfma_i32_16x16x64_i8 v[96:99], v[176:179], v[192:195], v[96:99]
	v_mfma_i32_16x16x64_i8 v[84:87], v[168:171], v[200:203], v[84:87]
	v_mfma_i32_16x16x64_i8 v[80:83], v[176:179], v[200:203], v[80:83]
	v_mfma_i32_16x16x64_i8 v[68:71], v[168:171], v[208:211], v[68:71]
	v_mfma_i32_16x16x64_i8 v[64:67], v[176:179], v[208:211], v[64:67]
	s_setprio 0
	s_barrier
	s_add_i32 s80, s72, s34
	v_lshl_add_u64 v[212:213], s[56:57], 0, v[132:133]
	s_mov_b32 m0, s80
	ds_read_b128 v[180:183], v155 offset:16384
	ds_read_b128 v[184:187], v155 offset:17408
	ds_read_b128 v[188:191], v155 offset:18432
	ds_read_b128 v[192:195], v155 offset:19456
	ds_read_b128 v[196:199], v155 offset:20480
	ds_read_b128 v[200:203], v155 offset:21504
	ds_read_b128 v[204:207], v155 offset:22528
	ds_read_b128 v[208:211], v155 offset:23552
	global_load_lds_dwordx4 v[212:213], off
	s_add_i32 m0, s80, 0x2000
	s_add_u32 s80, s56, 0x80000
	v_lshl_add_u64 v[214:215], s[56:57], 0, v[128:129]
	s_addc_u32 s81, s57, 0
	s_add_i32 s82, s73, s34
	global_load_lds_dwordx4 v[214:215], off
	v_lshl_add_u64 v[216:217], s[80:81], 0, v[132:133]
	s_mov_b32 m0, s82
	v_lshl_add_u64 v[218:219], s[58:59], 0, v[130:131]
	global_load_lds_dwordx4 v[216:217], off
	v_lshl_add_u64 v[216:217], s[80:81], 0, v[128:129]
	s_add_i32 m0, s82, 0x2000
	s_nop 0
	global_load_lds_dwordx4 v[216:217], off
	v_lshl_add_u64 v[216:217], s[58:59], 0, v[134:135]
	s_mov_b32 m0, s37
	s_nop 0
	global_load_lds_dwordx4 v[216:217], off
	s_mov_b32 m0, s45
	s_nop 0
	global_load_lds_dwordx4 v[218:219], off
	s_waitcnt vmcnt(8)
	s_waitcnt lgkmcnt(0)
	s_barrier
	s_setprio 1
	s_waitcnt lgkmcnt(0)
	v_mfma_i32_16x16x64_i8 v[60:63], v[144:147], v[180:183], 0
	v_mfma_i32_16x16x64_i8 v[56:59], v[156:159], v[180:183], 0
	v_mfma_i32_16x16x64_i8 v[44:47], v[144:147], v[188:191], 0
	v_mfma_i32_16x16x64_i8 v[40:43], v[156:159], v[188:191], 0
	v_mfma_i32_16x16x64_i8 v[28:31], v[144:147], v[196:199], 0
	v_mfma_i32_16x16x64_i8 v[24:27], v[156:159], v[196:199], 0
	v_mfma_i32_16x16x64_i8 v[12:15], v[144:147], v[204:207], 0
	v_mfma_i32_16x16x64_i8 v[8:11], v[156:159], v[204:207], 0
	v_mfma_i32_16x16x64_i8 v[60:63], v[148:151], v[184:187], v[60:63]
	v_mfma_i32_16x16x64_i8 v[56:59], v[160:163], v[184:187], v[56:59]
	v_mfma_i32_16x16x64_i8 v[44:47], v[148:151], v[192:195], v[44:47]
	v_mfma_i32_16x16x64_i8 v[40:43], v[160:163], v[192:195], v[40:43]
	v_mfma_i32_16x16x64_i8 v[28:31], v[148:151], v[200:203], v[28:31]
	v_mfma_i32_16x16x64_i8 v[24:27], v[160:163], v[200:203], v[24:27]
	v_mfma_i32_16x16x64_i8 v[12:15], v[148:151], v[208:211], v[12:15]
	v_mfma_i32_16x16x64_i8 v[8:11], v[160:163], v[208:211], v[8:11]
	s_setprio 0
	s_setprio 1
	v_mfma_i32_16x16x64_i8 v[52:55], v[164:167], v[180:183], 0
	v_mfma_i32_16x16x64_i8 v[48:51], v[172:175], v[180:183], 0
	v_mfma_i32_16x16x64_i8 v[36:39], v[164:167], v[188:191], 0
	v_mfma_i32_16x16x64_i8 v[32:35], v[172:175], v[188:191], 0
	v_mfma_i32_16x16x64_i8 v[20:23], v[164:167], v[196:199], 0
	v_mfma_i32_16x16x64_i8 v[16:19], v[172:175], v[196:199], 0
	v_mfma_i32_16x16x64_i8 v[4:7], v[164:167], v[204:207], 0
	v_mfma_i32_16x16x64_i8 v[0:3], v[172:175], v[204:207], 0
	v_mfma_i32_16x16x64_i8 v[52:55], v[168:171], v[184:187], v[52:55]
	v_mfma_i32_16x16x64_i8 v[48:51], v[176:179], v[184:187], v[48:51]
	v_mfma_i32_16x16x64_i8 v[36:39], v[168:171], v[192:195], v[36:39]
	v_mfma_i32_16x16x64_i8 v[32:35], v[176:179], v[192:195], v[32:35]
	v_mfma_i32_16x16x64_i8 v[20:23], v[168:171], v[200:203], v[20:23]
	v_mfma_i32_16x16x64_i8 v[16:19], v[176:179], v[200:203], v[16:19]
	v_mfma_i32_16x16x64_i8 v[4:7], v[168:171], v[208:211], v[4:7]
	v_mfma_i32_16x16x64_i8 v[0:3], v[176:179], v[208:211], v[0:3]
	s_setprio 0
	s_barrier
	s_add_i32 s80, 0, 0x18000
	s_add_i32 s81, 0, 0x1c000
	v_add_u32_e32 v160, s80, v152
	v_add_u32_e32 v176, s81, v152
	ds_read_b128 v[144:147], v160
	ds_read_b128 v[148:151], v160 offset:1024
	ds_read_b128 v[156:159], v160 offset:2048
	ds_read_b128 v[160:163], v160 offset:3072
	ds_read_b128 v[164:167], v176
	ds_read_b128 v[168:171], v176 offset:1024
	ds_read_b128 v[172:175], v176 offset:2048
	ds_read_b128 v[176:179], v176 offset:3072
	s_add_u32 s58, s58, 0x80000
	s_addc_u32 s59, s59, 0
	s_mov_b32 m0, s53
	v_lshl_add_u64 v[220:221], s[58:59], 0, v[134:135]
	ds_read_b128 v[180:183], v155 offset:32768
	ds_read_b128 v[184:187], v155 offset:33792
	ds_read_b128 v[188:191], v155 offset:34816
	ds_read_b128 v[192:195], v155 offset:35840
	ds_read_b128 v[196:199], v155 offset:36864
	ds_read_b128 v[200:203], v155 offset:37888
	ds_read_b128 v[204:207], v155 offset:38912
	ds_read_b128 v[208:211], v155 offset:39936
	global_load_lds_dwordx4 v[220:221], off
	v_lshl_add_u64 v[220:221], s[58:59], 0, v[130:131]
	s_mov_b32 m0, s60
	s_nop 0
	global_load_lds_dwordx4 v[220:221], off
	s_waitcnt vmcnt(8)
	s_waitcnt lgkmcnt(0)
	s_barrier
	s_setprio 1
	s_waitcnt lgkmcnt(0)
	v_mfma_i32_16x16x64_i8 v[124:127], v[144:147], v[180:183], v[124:127]
	v_mfma_i32_16x16x64_i8 v[120:123], v[156:159], v[180:183], v[120:123]
	v_mfma_i32_16x16x64_i8 v[108:111], v[144:147], v[188:191], v[108:111]
	v_mfma_i32_16x16x64_i8 v[104:107], v[156:159], v[188:191], v[104:107]
	v_mfma_i32_16x16x64_i8 v[92:95], v[144:147], v[196:199], v[92:95]
	v_mfma_i32_16x16x64_i8 v[88:91], v[156:159], v[196:199], v[88:91]
	v_mfma_i32_16x16x64_i8 v[76:79], v[144:147], v[204:207], v[76:79]
	v_mfma_i32_16x16x64_i8 v[72:75], v[156:159], v[204:207], v[72:75]
	v_mfma_i32_16x16x64_i8 v[124:127], v[148:151], v[184:187], v[124:127]
	v_mfma_i32_16x16x64_i8 v[120:123], v[160:163], v[184:187], v[120:123]
	v_mfma_i32_16x16x64_i8 v[108:111], v[148:151], v[192:195], v[108:111]
	v_mfma_i32_16x16x64_i8 v[104:107], v[160:163], v[192:195], v[104:107]
	v_mfma_i32_16x16x64_i8 v[92:95], v[148:151], v[200:203], v[92:95]
	v_mfma_i32_16x16x64_i8 v[88:91], v[160:163], v[200:203], v[88:91]
	v_mfma_i32_16x16x64_i8 v[76:79], v[148:151], v[208:211], v[76:79]
	v_mfma_i32_16x16x64_i8 v[72:75], v[160:163], v[208:211], v[72:75]
	s_setprio 0
	s_setprio 1
	v_mfma_i32_16x16x64_i8 v[116:119], v[164:167], v[180:183], v[116:119]
	v_mfma_i32_16x16x64_i8 v[112:115], v[172:175], v[180:183], v[112:115]
	v_mfma_i32_16x16x64_i8 v[100:103], v[164:167], v[188:191], v[100:103]
	v_mfma_i32_16x16x64_i8 v[96:99], v[172:175], v[188:191], v[96:99]
	v_mfma_i32_16x16x64_i8 v[84:87], v[164:167], v[196:199], v[84:87]
	v_mfma_i32_16x16x64_i8 v[80:83], v[172:175], v[196:199], v[80:83]
	v_mfma_i32_16x16x64_i8 v[68:71], v[164:167], v[204:207], v[68:71]
	v_mfma_i32_16x16x64_i8 v[64:67], v[172:175], v[204:207], v[64:67]
	v_mfma_i32_16x16x64_i8 v[116:119], v[168:171], v[184:187], v[116:119]
	v_mfma_i32_16x16x64_i8 v[112:115], v[176:179], v[184:187], v[112:115]
	v_mfma_i32_16x16x64_i8 v[100:103], v[168:171], v[192:195], v[100:103]
	v_mfma_i32_16x16x64_i8 v[96:99], v[176:179], v[192:195], v[96:99]
	v_mfma_i32_16x16x64_i8 v[84:87], v[168:171], v[200:203], v[84:87]
	v_mfma_i32_16x16x64_i8 v[80:83], v[176:179], v[200:203], v[80:83]
	v_mfma_i32_16x16x64_i8 v[68:71], v[168:171], v[208:211], v[68:71]
	v_mfma_i32_16x16x64_i8 v[64:67], v[176:179], v[208:211], v[64:67]
	s_setprio 0
	s_barrier
	s_add_i32 s58, s80, s34
	v_lshl_add_u64 v[212:213], v[212:213], 0, s[26:27]
	s_mov_b32 m0, s58
	ds_read_b128 v[180:183], v155 offset:49152
	ds_read_b128 v[184:187], v155 offset:50176
	ds_read_b128 v[188:191], v155 offset:51200
	ds_read_b128 v[192:195], v155 offset:52224
	ds_read_b128 v[196:199], v155 offset:53248
	ds_read_b128 v[200:203], v155 offset:54272
	ds_read_b128 v[204:207], v155 offset:55296
	ds_read_b128 v[208:211], v155 offset:56320
	global_load_lds_dwordx4 v[212:213], off
	s_add_i32 m0, s58, 0x2000
	s_add_u32 s56, s56, 0x80080
	v_lshl_add_u64 v[212:213], v[214:215], 0, s[26:27]
	s_addc_u32 s57, s57, 0
	s_add_i32 s58, s81, s34
	global_load_lds_dwordx4 v[212:213], off
	v_lshl_add_u64 v[212:213], s[56:57], 0, v[132:133]
	s_mov_b32 m0, s58
	s_nop 0
	global_load_lds_dwordx4 v[212:213], off
	v_lshl_add_u64 v[212:213], s[56:57], 0, v[128:129]
	s_add_i32 m0, s58, 0x2000
	s_nop 0
	global_load_lds_dwordx4 v[212:213], off
	v_lshl_add_u64 v[212:213], v[216:217], 0, s[26:27]
	s_mov_b32 m0, s63
	s_nop 0
	global_load_lds_dwordx4 v[212:213], off
	v_lshl_add_u64 v[212:213], v[218:219], 0, s[26:27]
	s_mov_b32 m0, s70
	s_nop 0
	global_load_lds_dwordx4 v[212:213], off
	s_waitcnt vmcnt(8)
	s_waitcnt lgkmcnt(0)
	s_barrier
	s_setprio 1
	s_waitcnt lgkmcnt(0)
	v_mfma_i32_16x16x64_i8 v[60:63], v[144:147], v[180:183], v[60:63]
	v_mfma_i32_16x16x64_i8 v[56:59], v[156:159], v[180:183], v[56:59]
	v_mfma_i32_16x16x64_i8 v[44:47], v[144:147], v[188:191], v[44:47]
	v_mfma_i32_16x16x64_i8 v[40:43], v[156:159], v[188:191], v[40:43]
	v_mfma_i32_16x16x64_i8 v[28:31], v[144:147], v[196:199], v[28:31]
	v_mfma_i32_16x16x64_i8 v[24:27], v[156:159], v[196:199], v[24:27]
	v_mfma_i32_16x16x64_i8 v[12:15], v[144:147], v[204:207], v[12:15]
	v_mfma_i32_16x16x64_i8 v[8:11], v[156:159], v[204:207], v[8:11]
	v_mfma_i32_16x16x64_i8 v[60:63], v[148:151], v[184:187], v[60:63]
	v_mfma_i32_16x16x64_i8 v[56:59], v[160:163], v[184:187], v[56:59]
	v_mfma_i32_16x16x64_i8 v[44:47], v[148:151], v[192:195], v[44:47]
	v_mfma_i32_16x16x64_i8 v[40:43], v[160:163], v[192:195], v[40:43]
	v_mfma_i32_16x16x64_i8 v[28:31], v[148:151], v[200:203], v[28:31]
	v_mfma_i32_16x16x64_i8 v[24:27], v[160:163], v[200:203], v[24:27]
	v_mfma_i32_16x16x64_i8 v[12:15], v[148:151], v[208:211], v[12:15]
	v_mfma_i32_16x16x64_i8 v[8:11], v[160:163], v[208:211], v[8:11]
	s_setprio 0
	s_setprio 1
	v_mfma_i32_16x16x64_i8 v[52:55], v[164:167], v[180:183], v[52:55]
	v_mfma_i32_16x16x64_i8 v[48:51], v[172:175], v[180:183], v[48:51]
	v_mfma_i32_16x16x64_i8 v[36:39], v[164:167], v[188:191], v[36:39]
	v_mfma_i32_16x16x64_i8 v[32:35], v[172:175], v[188:191], v[32:35]
	v_mfma_i32_16x16x64_i8 v[20:23], v[164:167], v[196:199], v[20:23]
	v_mfma_i32_16x16x64_i8 v[16:19], v[172:175], v[196:199], v[16:19]
	v_mfma_i32_16x16x64_i8 v[4:7], v[164:167], v[204:207], v[4:7]
	v_mfma_i32_16x16x64_i8 v[0:3], v[172:175], v[204:207], v[0:3]
	v_mfma_i32_16x16x64_i8 v[52:55], v[168:171], v[184:187], v[52:55]
	v_mfma_i32_16x16x64_i8 v[48:51], v[176:179], v[184:187], v[48:51]
	v_mfma_i32_16x16x64_i8 v[36:39], v[168:171], v[192:195], v[36:39]
	v_mfma_i32_16x16x64_i8 v[32:35], v[176:179], v[192:195], v[32:35]
	v_mfma_i32_16x16x64_i8 v[20:23], v[168:171], v[200:203], v[20:23]
	v_mfma_i32_16x16x64_i8 v[16:19], v[176:179], v[200:203], v[16:19]
	v_mfma_i32_16x16x64_i8 v[4:7], v[168:171], v[208:211], v[4:7]
	v_mfma_i32_16x16x64_i8 v[0:3], v[176:179], v[208:211], v[0:3]
	s_setprio 0
	s_barrier
	s_add_i32 s79, s79, 2
	s_add_u32 s54, s54, 0x100
	s_addc_u32 s55, s55, 0
	s_add_u32 s77, s77, 0x100
	s_addc_u32 s78, s78, 0
	s_cmp_gt_u32 s79, 29
	s_cbranch_scc1 .Lpost_p6

.Lpost_p6:
	s_and_b64 vcc, exec, s[28:29]
	s_cbranch_vccz .LBB0_774
	s_barrier

.LBB0_977:
	s_add_u32 s75, s46, 0x100
	s_addc_u32 s76, s47, 0
	s_mov_b32 s77, -2
	ds_read_b128 v[144:147], v153
	ds_read_b128 v[148:151], v153 offset:1024
	ds_read_b128 v[156:159], v153 offset:2048
	ds_read_b128 v[160:163], v153 offset:3072
	ds_read_b128 v[164:167], v154
	ds_read_b128 v[168:171], v154 offset:1024
	ds_read_b128 v[172:175], v154 offset:2048
	ds_read_b128 v[176:179], v154 offset:3072
	s_add_u32 s46, s40, 0x100
	s_addc_u32 s47, s41, 0
	s_cmpk_eq_i32 s77, 0x52
	s_cselect_b32 s51, s9, s47
	s_cselect_b32 s50, s8, s46
	s_cselect_b32 s49, s39, s76
	s_cselect_b32 s48, s38, s75
	v_lshl_add_u64 v[212:213], s[40:41], 0, v[136:137]
	s_add_i32 m0, s52, 0xc000
	ds_read_b128 v[180:183], v155
	ds_read_b128 v[184:187], v155 offset:1024
	ds_read_b128 v[188:191], v155 offset:2048
	ds_read_b128 v[192:195], v155 offset:3072
	ds_read_b128 v[196:199], v155 offset:4096
	ds_read_b128 v[200:203], v155 offset:5120
	ds_read_b128 v[204:207], v155 offset:6144
	ds_read_b128 v[208:211], v155 offset:7168
	global_load_lds_dwordx4 v[212:213], off
	v_lshl_add_u64 v[212:213], s[40:41], 0, v[138:139]
	s_add_i32 m0, s52, 0xe000
	s_nop 0
	global_load_lds_dwordx4 v[212:213], off
	s_waitcnt vmcnt(8)
	s_waitcnt lgkmcnt(0)
	s_barrier
	s_setprio 1
	s_waitcnt lgkmcnt(0)
	v_mfma_i32_16x16x64_i8 v[124:127], v[144:147], v[180:183], 0
	v_mfma_i32_16x16x64_i8 v[120:123], v[156:159], v[180:183], 0
	v_mfma_i32_16x16x64_i8 v[108:111], v[144:147], v[188:191], 0
	v_mfma_i32_16x16x64_i8 v[104:107], v[156:159], v[188:191], 0
	v_mfma_i32_16x16x64_i8 v[92:95], v[144:147], v[196:199], 0
	v_mfma_i32_16x16x64_i8 v[88:91], v[156:159], v[196:199], 0
	v_mfma_i32_16x16x64_i8 v[76:79], v[144:147], v[204:207], 0
	v_mfma_i32_16x16x64_i8 v[72:75], v[156:159], v[204:207], 0
	v_mfma_i32_16x16x64_i8 v[124:127], v[148:151], v[184:187], v[124:127]
	v_mfma_i32_16x16x64_i8 v[120:123], v[160:163], v[184:187], v[120:123]
	v_mfma_i32_16x16x64_i8 v[108:111], v[148:151], v[192:195], v[108:111]
	v_mfma_i32_16x16x64_i8 v[104:107], v[160:163], v[192:195], v[104:107]
	v_mfma_i32_16x16x64_i8 v[92:95], v[148:151], v[200:203], v[92:95]
	v_mfma_i32_16x16x64_i8 v[88:91], v[160:163], v[200:203], v[88:91]
	v_mfma_i32_16x16x64_i8 v[76:79], v[148:151], v[208:211], v[76:79]
	v_mfma_i32_16x16x64_i8 v[72:75], v[160:163], v[208:211], v[72:75]
	s_setprio 0
	s_setprio 1
	v_mfma_i32_16x16x64_i8 v[116:119], v[164:167], v[180:183], 0
	v_mfma_i32_16x16x64_i8 v[112:115], v[172:175], v[180:183], 0
	v_mfma_i32_16x16x64_i8 v[100:103], v[164:167], v[188:191], 0
	v_mfma_i32_16x16x64_i8 v[96:99], v[172:175], v[188:191], 0
	v_mfma_i32_16x16x64_i8 v[84:87], v[164:167], v[196:199], 0
	v_mfma_i32_16x16x64_i8 v[80:83], v[172:175], v[196:199], 0
	v_mfma_i32_16x16x64_i8 v[68:71], v[164:167], v[204:207], 0
	v_mfma_i32_16x16x64_i8 v[64:67], v[172:175], v[204:207], 0
	v_mfma_i32_16x16x64_i8 v[116:119], v[168:171], v[184:187], v[116:119]
	v_mfma_i32_16x16x64_i8 v[112:115], v[176:179], v[184:187], v[112:115]
	v_mfma_i32_16x16x64_i8 v[100:103], v[168:171], v[192:195], v[100:103]
	v_mfma_i32_16x16x64_i8 v[96:99], v[176:179], v[192:195], v[96:99]
	v_mfma_i32_16x16x64_i8 v[84:87], v[168:171], v[200:203], v[84:87]
	v_mfma_i32_16x16x64_i8 v[80:83], v[176:179], v[200:203], v[80:83]
	v_mfma_i32_16x16x64_i8 v[68:71], v[168:171], v[208:211], v[68:71]
	v_mfma_i32_16x16x64_i8 v[64:67], v[176:179], v[208:211], v[64:67]
	s_setprio 0
	s_barrier
	s_add_i32 s40, s61, s35
	v_lshl_add_u64 v[212:213], s[48:49], 0, v[132:133]
	s_mov_b32 m0, s40
	ds_read_b128 v[180:183], v155 offset:16384
	ds_read_b128 v[184:187], v155 offset:17408
	ds_read_b128 v[188:191], v155 offset:18432
	ds_read_b128 v[192:195], v155 offset:19456
	ds_read_b128 v[196:199], v155 offset:20480
	ds_read_b128 v[200:203], v155 offset:21504
	ds_read_b128 v[204:207], v155 offset:22528
	ds_read_b128 v[208:211], v155 offset:23552
	global_load_lds_dwordx4 v[212:213], off
	s_add_i32 m0, s40, 0x2000
	s_add_u32 s40, s48, 0x158000
	v_lshl_add_u64 v[214:215], s[48:49], 0, v[128:129]
	s_addc_u32 s41, s49, 0
	s_add_i32 s78, s62, s35
	global_load_lds_dwordx4 v[214:215], off
	v_lshl_add_u64 v[216:217], s[40:41], 0, v[132:133]
	s_mov_b32 m0, s78
	v_lshl_add_u64 v[218:219], s[50:51], 0, v[130:131]
	global_load_lds_dwordx4 v[216:217], off
	v_lshl_add_u64 v[216:217], s[40:41], 0, v[128:129]
	s_add_i32 m0, s78, 0x2000
	s_nop 0
	global_load_lds_dwordx4 v[216:217], off
	v_lshl_add_u64 v[216:217], s[50:51], 0, v[134:135]
	s_mov_b32 m0, s52
	s_nop 0
	global_load_lds_dwordx4 v[216:217], off
	s_mov_b32 m0, s53
	s_nop 0
	global_load_lds_dwordx4 v[218:219], off
	s_waitcnt vmcnt(8)
	s_waitcnt lgkmcnt(0)
	s_barrier
	s_setprio 1
	s_waitcnt lgkmcnt(0)
	v_mfma_i32_16x16x64_i8 v[60:63], v[144:147], v[180:183], 0
	v_mfma_i32_16x16x64_i8 v[56:59], v[156:159], v[180:183], 0
	v_mfma_i32_16x16x64_i8 v[44:47], v[144:147], v[188:191], 0
	v_mfma_i32_16x16x64_i8 v[40:43], v[156:159], v[188:191], 0
	v_mfma_i32_16x16x64_i8 v[28:31], v[144:147], v[196:199], 0
	v_mfma_i32_16x16x64_i8 v[24:27], v[156:159], v[196:199], 0
	v_mfma_i32_16x16x64_i8 v[12:15], v[144:147], v[204:207], 0
	v_mfma_i32_16x16x64_i8 v[8:11], v[156:159], v[204:207], 0
	v_mfma_i32_16x16x64_i8 v[60:63], v[148:151], v[184:187], v[60:63]
	v_mfma_i32_16x16x64_i8 v[56:59], v[160:163], v[184:187], v[56:59]
	v_mfma_i32_16x16x64_i8 v[44:47], v[148:151], v[192:195], v[44:47]
	v_mfma_i32_16x16x64_i8 v[40:43], v[160:163], v[192:195], v[40:43]
	v_mfma_i32_16x16x64_i8 v[28:31], v[148:151], v[200:203], v[28:31]
	v_mfma_i32_16x16x64_i8 v[24:27], v[160:163], v[200:203], v[24:27]
	v_mfma_i32_16x16x64_i8 v[12:15], v[148:151], v[208:211], v[12:15]
	v_mfma_i32_16x16x64_i8 v[8:11], v[160:163], v[208:211], v[8:11]
	s_setprio 0
	s_setprio 1
	v_mfma_i32_16x16x64_i8 v[52:55], v[164:167], v[180:183], 0
	v_mfma_i32_16x16x64_i8 v[48:51], v[172:175], v[180:183], 0
	v_mfma_i32_16x16x64_i8 v[36:39], v[164:167], v[188:191], 0
	v_mfma_i32_16x16x64_i8 v[32:35], v[172:175], v[188:191], 0
	v_mfma_i32_16x16x64_i8 v[20:23], v[164:167], v[196:199], 0
	v_mfma_i32_16x16x64_i8 v[16:19], v[172:175], v[196:199], 0
	v_mfma_i32_16x16x64_i8 v[4:7], v[164:167], v[204:207], 0
	v_mfma_i32_16x16x64_i8 v[0:3], v[172:175], v[204:207], 0
	v_mfma_i32_16x16x64_i8 v[52:55], v[168:171], v[184:187], v[52:55]
	v_mfma_i32_16x16x64_i8 v[48:51], v[176:179], v[184:187], v[48:51]
	v_mfma_i32_16x16x64_i8 v[36:39], v[168:171], v[192:195], v[36:39]
	v_mfma_i32_16x16x64_i8 v[32:35], v[176:179], v[192:195], v[32:35]
	v_mfma_i32_16x16x64_i8 v[20:23], v[168:171], v[200:203], v[20:23]
	v_mfma_i32_16x16x64_i8 v[16:19], v[176:179], v[200:203], v[16:19]
	v_mfma_i32_16x16x64_i8 v[4:7], v[168:171], v[208:211], v[4:7]
	v_mfma_i32_16x16x64_i8 v[0:3], v[176:179], v[208:211], v[0:3]
	s_setprio 0
	s_barrier
	s_add_i32 s78, 0, 0x18000
	s_add_i32 s79, 0, 0x1c000
	v_add_u32_e32 v160, s78, v152
	v_add_u32_e32 v176, s79, v152
	ds_read_b128 v[144:147], v160
	ds_read_b128 v[148:151], v160 offset:1024
	ds_read_b128 v[156:159], v160 offset:2048
	ds_read_b128 v[160:163], v160 offset:3072
	ds_read_b128 v[164:167], v176
	ds_read_b128 v[168:171], v176 offset:1024
	ds_read_b128 v[172:175], v176 offset:2048
	ds_read_b128 v[176:179], v176 offset:3072
	s_add_u32 s40, s50, 0x158000
	s_addc_u32 s41, s51, 0
	s_mov_b32 m0, s54
	v_lshl_add_u64 v[220:221], s[40:41], 0, v[134:135]
	ds_read_b128 v[180:183], v155 offset:32768
	ds_read_b128 v[184:187], v155 offset:33792
	ds_read_b128 v[188:191], v155 offset:34816
	ds_read_b128 v[192:195], v155 offset:35840
	ds_read_b128 v[196:199], v155 offset:36864
	ds_read_b128 v[200:203], v155 offset:37888
	ds_read_b128 v[204:207], v155 offset:38912
	ds_read_b128 v[208:211], v155 offset:39936
	global_load_lds_dwordx4 v[220:221], off
	v_lshl_add_u64 v[220:221], s[40:41], 0, v[130:131]
	s_mov_b32 m0, s55
	s_nop 0
	global_load_lds_dwordx4 v[220:221], off
	s_waitcnt vmcnt(8)
	s_waitcnt lgkmcnt(0)
	s_barrier
	s_setprio 1
	s_waitcnt lgkmcnt(0)
	v_mfma_i32_16x16x64_i8 v[124:127], v[144:147], v[180:183], v[124:127]
	v_mfma_i32_16x16x64_i8 v[120:123], v[156:159], v[180:183], v[120:123]
	v_mfma_i32_16x16x64_i8 v[108:111], v[144:147], v[188:191], v[108:111]
	v_mfma_i32_16x16x64_i8 v[104:107], v[156:159], v[188:191], v[104:107]
	v_mfma_i32_16x16x64_i8 v[92:95], v[144:147], v[196:199], v[92:95]
	v_mfma_i32_16x16x64_i8 v[88:91], v[156:159], v[196:199], v[88:91]
	v_mfma_i32_16x16x64_i8 v[76:79], v[144:147], v[204:207], v[76:79]
	v_mfma_i32_16x16x64_i8 v[72:75], v[156:159], v[204:207], v[72:75]
	v_mfma_i32_16x16x64_i8 v[124:127], v[148:151], v[184:187], v[124:127]
	v_mfma_i32_16x16x64_i8 v[120:123], v[160:163], v[184:187], v[120:123]
	v_mfma_i32_16x16x64_i8 v[108:111], v[148:151], v[192:195], v[108:111]
	v_mfma_i32_16x16x64_i8 v[104:107], v[160:163], v[192:195], v[104:107]
	v_mfma_i32_16x16x64_i8 v[92:95], v[148:151], v[200:203], v[92:95]
	v_mfma_i32_16x16x64_i8 v[88:91], v[160:163], v[200:203], v[88:91]
	v_mfma_i32_16x16x64_i8 v[76:79], v[148:151], v[208:211], v[76:79]
	v_mfma_i32_16x16x64_i8 v[72:75], v[160:163], v[208:211], v[72:75]
	s_setprio 0
	s_setprio 1
	v_mfma_i32_16x16x64_i8 v[116:119], v[164:167], v[180:183], v[116:119]
	v_mfma_i32_16x16x64_i8 v[112:115], v[172:175], v[180:183], v[112:115]
	v_mfma_i32_16x16x64_i8 v[100:103], v[164:167], v[188:191], v[100:103]
	v_mfma_i32_16x16x64_i8 v[96:99], v[172:175], v[188:191], v[96:99]
	v_mfma_i32_16x16x64_i8 v[84:87], v[164:167], v[196:199], v[84:87]
	v_mfma_i32_16x16x64_i8 v[80:83], v[172:175], v[196:199], v[80:83]
	v_mfma_i32_16x16x64_i8 v[68:71], v[164:167], v[204:207], v[68:71]
	v_mfma_i32_16x16x64_i8 v[64:67], v[172:175], v[204:207], v[64:67]
	v_mfma_i32_16x16x64_i8 v[116:119], v[168:171], v[184:187], v[116:119]
	v_mfma_i32_16x16x64_i8 v[112:115], v[176:179], v[184:187], v[112:115]
	v_mfma_i32_16x16x64_i8 v[100:103], v[168:171], v[192:195], v[100:103]
	v_mfma_i32_16x16x64_i8 v[96:99], v[176:179], v[192:195], v[96:99]
	v_mfma_i32_16x16x64_i8 v[84:87], v[168:171], v[200:203], v[84:87]
	v_mfma_i32_16x16x64_i8 v[80:83], v[176:179], v[200:203], v[80:83]
	v_mfma_i32_16x16x64_i8 v[68:71], v[168:171], v[208:211], v[68:71]
	v_mfma_i32_16x16x64_i8 v[64:67], v[176:179], v[208:211], v[64:67]
	s_setprio 0
	s_barrier
	s_add_i32 s40, s78, s35
	v_lshl_add_u64 v[212:213], v[212:213], 0, s[20:21]
	s_mov_b32 m0, s40
	ds_read_b128 v[180:183], v155 offset:49152
	ds_read_b128 v[184:187], v155 offset:50176
	ds_read_b128 v[188:191], v155 offset:51200
	ds_read_b128 v[192:195], v155 offset:52224
	ds_read_b128 v[196:199], v155 offset:53248
	ds_read_b128 v[200:203], v155 offset:54272
	ds_read_b128 v[204:207], v155 offset:55296
	ds_read_b128 v[208:211], v155 offset:56320
	global_load_lds_dwordx4 v[212:213], off
	s_add_i32 m0, s40, 0x2000
	s_add_u32 s40, s48, 0x158080
	v_lshl_add_u64 v[212:213], v[214:215], 0, s[20:21]
	s_addc_u32 s41, s49, 0
	s_add_i32 s48, s79, s35
	global_load_lds_dwordx4 v[212:213], off
	v_lshl_add_u64 v[212:213], s[40:41], 0, v[132:133]
	s_mov_b32 m0, s48
	s_nop 0
	global_load_lds_dwordx4 v[212:213], off
	v_lshl_add_u64 v[212:213], s[40:41], 0, v[128:129]
	s_add_i32 m0, s48, 0x2000
	s_nop 0
	global_load_lds_dwordx4 v[212:213], off
	v_lshl_add_u64 v[212:213], v[216:217], 0, s[20:21]
	s_mov_b32 m0, s58
	s_nop 0
	global_load_lds_dwordx4 v[212:213], off
	v_lshl_add_u64 v[212:213], v[218:219], 0, s[20:21]
	s_mov_b32 m0, s59
	s_nop 0
	global_load_lds_dwordx4 v[212:213], off
	s_waitcnt vmcnt(8)
	s_waitcnt lgkmcnt(0)
	s_barrier
	s_setprio 1
	s_waitcnt lgkmcnt(0)
	v_mfma_i32_16x16x64_i8 v[60:63], v[144:147], v[180:183], v[60:63]
	v_mfma_i32_16x16x64_i8 v[56:59], v[156:159], v[180:183], v[56:59]
	v_mfma_i32_16x16x64_i8 v[44:47], v[144:147], v[188:191], v[44:47]
	v_mfma_i32_16x16x64_i8 v[40:43], v[156:159], v[188:191], v[40:43]
	v_mfma_i32_16x16x64_i8 v[28:31], v[144:147], v[196:199], v[28:31]
	v_mfma_i32_16x16x64_i8 v[24:27], v[156:159], v[196:199], v[24:27]
	v_mfma_i32_16x16x64_i8 v[12:15], v[144:147], v[204:207], v[12:15]
	v_mfma_i32_16x16x64_i8 v[8:11], v[156:159], v[204:207], v[8:11]
	v_mfma_i32_16x16x64_i8 v[60:63], v[148:151], v[184:187], v[60:63]
	v_mfma_i32_16x16x64_i8 v[56:59], v[160:163], v[184:187], v[56:59]
	v_mfma_i32_16x16x64_i8 v[44:47], v[148:151], v[192:195], v[44:47]
	v_mfma_i32_16x16x64_i8 v[40:43], v[160:163], v[192:195], v[40:43]
	v_mfma_i32_16x16x64_i8 v[28:31], v[148:151], v[200:203], v[28:31]
	v_mfma_i32_16x16x64_i8 v[24:27], v[160:163], v[200:203], v[24:27]
	v_mfma_i32_16x16x64_i8 v[12:15], v[148:151], v[208:211], v[12:15]
	v_mfma_i32_16x16x64_i8 v[8:11], v[160:163], v[208:211], v[8:11]
	s_setprio 0
	s_setprio 1
	v_mfma_i32_16x16x64_i8 v[52:55], v[164:167], v[180:183], v[52:55]
	v_mfma_i32_16x16x64_i8 v[48:51], v[172:175], v[180:183], v[48:51]
	v_mfma_i32_16x16x64_i8 v[36:39], v[164:167], v[188:191], v[36:39]
	v_mfma_i32_16x16x64_i8 v[32:35], v[172:175], v[188:191], v[32:35]
	v_mfma_i32_16x16x64_i8 v[20:23], v[164:167], v[196:199], v[20:23]
	v_mfma_i32_16x16x64_i8 v[16:19], v[172:175], v[196:199], v[16:19]
	v_mfma_i32_16x16x64_i8 v[4:7], v[164:167], v[204:207], v[4:7]
	v_mfma_i32_16x16x64_i8 v[0:3], v[172:175], v[204:207], v[0:3]
	v_mfma_i32_16x16x64_i8 v[52:55], v[168:171], v[184:187], v[52:55]
	v_mfma_i32_16x16x64_i8 v[48:51], v[176:179], v[184:187], v[48:51]
	v_mfma_i32_16x16x64_i8 v[36:39], v[168:171], v[192:195], v[36:39]
	v_mfma_i32_16x16x64_i8 v[32:35], v[176:179], v[192:195], v[32:35]
	v_mfma_i32_16x16x64_i8 v[20:23], v[168:171], v[200:203], v[20:23]
	v_mfma_i32_16x16x64_i8 v[16:19], v[176:179], v[200:203], v[16:19]
	v_mfma_i32_16x16x64_i8 v[4:7], v[168:171], v[208:211], v[4:7]
	v_mfma_i32_16x16x64_i8 v[0:3], v[176:179], v[208:211], v[0:3]
	s_setprio 0
	s_barrier
	s_add_i32 s77, s77, 2
	s_add_u32 s75, s75, 0x100
	s_addc_u32 s76, s76, 0
	s_cmpk_gt_u32 s77, 0x53
	s_mov_b64 s[40:41], s[46:47]
	s_cbranch_scc1 .Lpost_p7
.LBB0_978:
	ds_read_b128 v[144:147], v153
	ds_read_b128 v[148:151], v153 offset:1024
	ds_read_b128 v[156:159], v153 offset:2048
	ds_read_b128 v[160:163], v153 offset:3072
	ds_read_b128 v[164:167], v154
	ds_read_b128 v[168:171], v154 offset:1024
	ds_read_b128 v[172:175], v154 offset:2048
	ds_read_b128 v[176:179], v154 offset:3072
	s_add_u32 s46, s40, 0x100
	s_addc_u32 s47, s41, 0
	s_cmpk_eq_i32 s77, 0x52
	s_cselect_b32 s51, s9, s47
	s_cselect_b32 s50, s8, s46
	s_cselect_b32 s49, s39, s76
	s_cselect_b32 s48, s38, s75
	v_lshl_add_u64 v[212:213], s[40:41], 0, v[136:137]
	s_add_i32 m0, s52, 0xc000
	ds_read_b128 v[180:183], v155
	ds_read_b128 v[184:187], v155 offset:1024
	ds_read_b128 v[188:191], v155 offset:2048
	ds_read_b128 v[192:195], v155 offset:3072
	ds_read_b128 v[196:199], v155 offset:4096
	ds_read_b128 v[200:203], v155 offset:5120
	ds_read_b128 v[204:207], v155 offset:6144
	ds_read_b128 v[208:211], v155 offset:7168
	global_load_lds_dwordx4 v[212:213], off
	v_lshl_add_u64 v[212:213], s[40:41], 0, v[138:139]
	s_add_i32 m0, s52, 0xe000
	s_nop 0
	global_load_lds_dwordx4 v[212:213], off
	s_waitcnt vmcnt(8)
	s_waitcnt lgkmcnt(0)
	s_barrier
	s_setprio 1
	s_waitcnt lgkmcnt(0)
	v_mfma_i32_16x16x64_i8 v[124:127], v[144:147], v[180:183], v[124:127]
	v_mfma_i32_16x16x64_i8 v[120:123], v[156:159], v[180:183], v[120:123]
	v_mfma_i32_16x16x64_i8 v[108:111], v[144:147], v[188:191], v[108:111]
	v_mfma_i32_16x16x64_i8 v[104:107], v[156:159], v[188:191], v[104:107]
	v_mfma_i32_16x16x64_i8 v[92:95], v[144:147], v[196:199], v[92:95]
	v_mfma_i32_16x16x64_i8 v[88:91], v[156:159], v[196:199], v[88:91]
	v_mfma_i32_16x16x64_i8 v[76:79], v[144:147], v[204:207], v[76:79]
	v_mfma_i32_16x16x64_i8 v[72:75], v[156:159], v[204:207], v[72:75]
	v_mfma_i32_16x16x64_i8 v[124:127], v[148:151], v[184:187], v[124:127]
	v_mfma_i32_16x16x64_i8 v[120:123], v[160:163], v[184:187], v[120:123]
	v_mfma_i32_16x16x64_i8 v[108:111], v[148:151], v[192:195], v[108:111]
	v_mfma_i32_16x16x64_i8 v[104:107], v[160:163], v[192:195], v[104:107]
	v_mfma_i32_16x16x64_i8 v[92:95], v[148:151], v[200:203], v[92:95]
	v_mfma_i32_16x16x64_i8 v[88:91], v[160:163], v[200:203], v[88:91]
	v_mfma_i32_16x16x64_i8 v[76:79], v[148:151], v[208:211], v[76:79]
	v_mfma_i32_16x16x64_i8 v[72:75], v[160:163], v[208:211], v[72:75]
	s_setprio 0
	s_setprio 1
	v_mfma_i32_16x16x64_i8 v[116:119], v[164:167], v[180:183], v[116:119]
	v_mfma_i32_16x16x64_i8 v[112:115], v[172:175], v[180:183], v[112:115]
	v_mfma_i32_16x16x64_i8 v[100:103], v[164:167], v[188:191], v[100:103]
	v_mfma_i32_16x16x64_i8 v[96:99], v[172:175], v[188:191], v[96:99]
	v_mfma_i32_16x16x64_i8 v[84:87], v[164:167], v[196:199], v[84:87]
	v_mfma_i32_16x16x64_i8 v[80:83], v[172:175], v[196:199], v[80:83]
	v_mfma_i32_16x16x64_i8 v[68:71], v[164:167], v[204:207], v[68:71]
	v_mfma_i32_16x16x64_i8 v[64:67], v[172:175], v[204:207], v[64:67]
	v_mfma_i32_16x16x64_i8 v[116:119], v[168:171], v[184:187], v[116:119]
	v_mfma_i32_16x16x64_i8 v[112:115], v[176:179], v[184:187], v[112:115]
	v_mfma_i32_16x16x64_i8 v[100:103], v[168:171], v[192:195], v[100:103]
	v_mfma_i32_16x16x64_i8 v[96:99], v[176:179], v[192:195], v[96:99]
	v_mfma_i32_16x16x64_i8 v[84:87], v[168:171], v[200:203], v[84:87]
	v_mfma_i32_16x16x64_i8 v[80:83], v[176:179], v[200:203], v[80:83]
	v_mfma_i32_16x16x64_i8 v[68:71], v[168:171], v[208:211], v[68:71]
	v_mfma_i32_16x16x64_i8 v[64:67], v[176:179], v[208:211], v[64:67]
	s_setprio 0
	s_barrier
	s_add_i32 s40, s61, s35
	v_lshl_add_u64 v[212:213], s[48:49], 0, v[132:133]
	s_mov_b32 m0, s40
	ds_read_b128 v[180:183], v155 offset:16384
	ds_read_b128 v[184:187], v155 offset:17408
	ds_read_b128 v[188:191], v155 offset:18432
	ds_read_b128 v[192:195], v155 offset:19456
	ds_read_b128 v[196:199], v155 offset:20480
	ds_read_b128 v[200:203], v155 offset:21504
	ds_read_b128 v[204:207], v155 offset:22528
	ds_read_b128 v[208:211], v155 offset:23552
	global_load_lds_dwordx4 v[212:213], off
	s_add_i32 m0, s40, 0x2000
	s_add_u32 s40, s48, 0x158000
	v_lshl_add_u64 v[214:215], s[48:49], 0, v[128:129]
	s_addc_u32 s41, s49, 0
	s_add_i32 s78, s62, s35
	global_load_lds_dwordx4 v[214:215], off
	v_lshl_add_u64 v[216:217], s[40:41], 0, v[132:133]
	s_mov_b32 m0, s78
	v_lshl_add_u64 v[218:219], s[50:51], 0, v[130:131]
	global_load_lds_dwordx4 v[216:217], off
	v_lshl_add_u64 v[216:217], s[40:41], 0, v[128:129]
	s_add_i32 m0, s78, 0x2000
	s_nop 0
	global_load_lds_dwordx4 v[216:217], off
	v_lshl_add_u64 v[216:217], s[50:51], 0, v[134:135]
	s_mov_b32 m0, s52
	s_nop 0
	global_load_lds_dwordx4 v[216:217], off
	s_mov_b32 m0, s53
	s_nop 0
	global_load_lds_dwordx4 v[218:219], off
	s_waitcnt vmcnt(8)
	s_waitcnt lgkmcnt(0)
	s_barrier
	s_setprio 1
	s_waitcnt lgkmcnt(0)
	v_mfma_i32_16x16x64_i8 v[60:63], v[144:147], v[180:183], v[60:63]
	v_mfma_i32_16x16x64_i8 v[56:59], v[156:159], v[180:183], v[56:59]
	v_mfma_i32_16x16x64_i8 v[44:47], v[144:147], v[188:191], v[44:47]
	v_mfma_i32_16x16x64_i8 v[40:43], v[156:159], v[188:191], v[40:43]
	v_mfma_i32_16x16x64_i8 v[28:31], v[144:147], v[196:199], v[28:31]
	v_mfma_i32_16x16x64_i8 v[24:27], v[156:159], v[196:199], v[24:27]
	v_mfma_i32_16x16x64_i8 v[12:15], v[144:147], v[204:207], v[12:15]
	v_mfma_i32_16x16x64_i8 v[8:11], v[156:159], v[204:207], v[8:11]
	v_mfma_i32_16x16x64_i8 v[60:63], v[148:151], v[184:187], v[60:63]
	v_mfma_i32_16x16x64_i8 v[56:59], v[160:163], v[184:187], v[56:59]
	v_mfma_i32_16x16x64_i8 v[44:47], v[148:151], v[192:195], v[44:47]
	v_mfma_i32_16x16x64_i8 v[40:43], v[160:163], v[192:195], v[40:43]
	v_mfma_i32_16x16x64_i8 v[28:31], v[148:151], v[200:203], v[28:31]
	v_mfma_i32_16x16x64_i8 v[24:27], v[160:163], v[200:203], v[24:27]
	v_mfma_i32_16x16x64_i8 v[12:15], v[148:151], v[208:211], v[12:15]
	v_mfma_i32_16x16x64_i8 v[8:11], v[160:163], v[208:211], v[8:11]
	s_setprio 0
	s_setprio 1
	v_mfma_i32_16x16x64_i8 v[52:55], v[164:167], v[180:183], v[52:55]
	v_mfma_i32_16x16x64_i8 v[48:51], v[172:175], v[180:183], v[48:51]
	v_mfma_i32_16x16x64_i8 v[36:39], v[164:167], v[188:191], v[36:39]
	v_mfma_i32_16x16x64_i8 v[32:35], v[172:175], v[188:191], v[32:35]
	v_mfma_i32_16x16x64_i8 v[20:23], v[164:167], v[196:199], v[20:23]
	v_mfma_i32_16x16x64_i8 v[16:19], v[172:175], v[196:199], v[16:19]
	v_mfma_i32_16x16x64_i8 v[4:7], v[164:167], v[204:207], v[4:7]
	v_mfma_i32_16x16x64_i8 v[0:3], v[172:175], v[204:207], v[0:3]
	v_mfma_i32_16x16x64_i8 v[52:55], v[168:171], v[184:187], v[52:55]
	v_mfma_i32_16x16x64_i8 v[48:51], v[176:179], v[184:187], v[48:51]
	v_mfma_i32_16x16x64_i8 v[36:39], v[168:171], v[192:195], v[36:39]
	v_mfma_i32_16x16x64_i8 v[32:35], v[176:179], v[192:195], v[32:35]
	v_mfma_i32_16x16x64_i8 v[20:23], v[168:171], v[200:203], v[20:23]
	v_mfma_i32_16x16x64_i8 v[16:19], v[176:179], v[200:203], v[16:19]
	v_mfma_i32_16x16x64_i8 v[4:7], v[168:171], v[208:211], v[4:7]
	v_mfma_i32_16x16x64_i8 v[0:3], v[176:179], v[208:211], v[0:3]
	s_setprio 0
	s_barrier
	s_add_i32 s78, 0, 0x18000
	s_add_i32 s79, 0, 0x1c000
	v_add_u32_e32 v160, s78, v152
	v_add_u32_e32 v176, s79, v152
	ds_read_b128 v[144:147], v160
	ds_read_b128 v[148:151], v160 offset:1024
	ds_read_b128 v[156:159], v160 offset:2048
	ds_read_b128 v[160:163], v160 offset:3072
	ds_read_b128 v[164:167], v176
	ds_read_b128 v[168:171], v176 offset:1024
	ds_read_b128 v[172:175], v176 offset:2048
	ds_read_b128 v[176:179], v176 offset:3072
	s_add_u32 s40, s50, 0x158000
	s_addc_u32 s41, s51, 0
	s_mov_b32 m0, s54
	v_lshl_add_u64 v[220:221], s[40:41], 0, v[134:135]
	ds_read_b128 v[180:183], v155 offset:32768
	ds_read_b128 v[184:187], v155 offset:33792
	ds_read_b128 v[188:191], v155 offset:34816
	ds_read_b128 v[192:195], v155 offset:35840
	ds_read_b128 v[196:199], v155 offset:36864
	ds_read_b128 v[200:203], v155 offset:37888
	ds_read_b128 v[204:207], v155 offset:38912
	ds_read_b128 v[208:211], v155 offset:39936
	global_load_lds_dwordx4 v[220:221], off
	v_lshl_add_u64 v[220:221], s[40:41], 0, v[130:131]
	s_mov_b32 m0, s55
	s_nop 0
	global_load_lds_dwordx4 v[220:221], off
	s_waitcnt vmcnt(8)
	s_waitcnt lgkmcnt(0)
	s_barrier
	s_setprio 1
	s_waitcnt lgkmcnt(0)
	v_mfma_i32_16x16x64_i8 v[124:127], v[144:147], v[180:183], v[124:127]
	v_mfma_i32_16x16x64_i8 v[120:123], v[156:159], v[180:183], v[120:123]
	v_mfma_i32_16x16x64_i8 v[108:111], v[144:147], v[188:191], v[108:111]
	v_mfma_i32_16x16x64_i8 v[104:107], v[156:159], v[188:191], v[104:107]
	v_mfma_i32_16x16x64_i8 v[92:95], v[144:147], v[196:199], v[92:95]
	v_mfma_i32_16x16x64_i8 v[88:91], v[156:159], v[196:199], v[88:91]
	v_mfma_i32_16x16x64_i8 v[76:79], v[144:147], v[204:207], v[76:79]
	v_mfma_i32_16x16x64_i8 v[72:75], v[156:159], v[204:207], v[72:75]
	v_mfma_i32_16x16x64_i8 v[124:127], v[148:151], v[184:187], v[124:127]
	v_mfma_i32_16x16x64_i8 v[120:123], v[160:163], v[184:187], v[120:123]
	v_mfma_i32_16x16x64_i8 v[108:111], v[148:151], v[192:195], v[108:111]
	v_mfma_i32_16x16x64_i8 v[104:107], v[160:163], v[192:195], v[104:107]
	v_mfma_i32_16x16x64_i8 v[92:95], v[148:151], v[200:203], v[92:95]
	v_mfma_i32_16x16x64_i8 v[88:91], v[160:163], v[200:203], v[88:91]
	v_mfma_i32_16x16x64_i8 v[76:79], v[148:151], v[208:211], v[76:79]
	v_mfma_i32_16x16x64_i8 v[72:75], v[160:163], v[208:211], v[72:75]
	s_setprio 0
	s_setprio 1
	v_mfma_i32_16x16x64_i8 v[116:119], v[164:167], v[180:183], v[116:119]
	v_mfma_i32_16x16x64_i8 v[112:115], v[172:175], v[180:183], v[112:115]
	v_mfma_i32_16x16x64_i8 v[100:103], v[164:167], v[188:191], v[100:103]
	v_mfma_i32_16x16x64_i8 v[96:99], v[172:175], v[188:191], v[96:99]
	v_mfma_i32_16x16x64_i8 v[84:87], v[164:167], v[196:199], v[84:87]
	v_mfma_i32_16x16x64_i8 v[80:83], v[172:175], v[196:199], v[80:83]
	v_mfma_i32_16x16x64_i8 v[68:71], v[164:167], v[204:207], v[68:71]
	v_mfma_i32_16x16x64_i8 v[64:67], v[172:175], v[204:207], v[64:67]
	v_mfma_i32_16x16x64_i8 v[116:119], v[168:171], v[184:187], v[116:119]
	v_mfma_i32_16x16x64_i8 v[112:115], v[176:179], v[184:187], v[112:115]
	v_mfma_i32_16x16x64_i8 v[100:103], v[168:171], v[192:195], v[100:103]
	v_mfma_i32_16x16x64_i8 v[96:99], v[176:179], v[192:195], v[96:99]
	v_mfma_i32_16x16x64_i8 v[84:87], v[168:171], v[200:203], v[84:87]
	v_mfma_i32_16x16x64_i8 v[80:83], v[176:179], v[200:203], v[80:83]
	v_mfma_i32_16x16x64_i8 v[68:71], v[168:171], v[208:211], v[68:71]
	v_mfma_i32_16x16x64_i8 v[64:67], v[176:179], v[208:211], v[64:67]
	s_setprio 0
	s_barrier
	s_add_i32 s40, s78, s35
	v_lshl_add_u64 v[212:213], v[212:213], 0, s[20:21]
	s_mov_b32 m0, s40
	ds_read_b128 v[180:183], v155 offset:49152
	ds_read_b128 v[184:187], v155 offset:50176
	ds_read_b128 v[188:191], v155 offset:51200
	ds_read_b128 v[192:195], v155 offset:52224
	ds_read_b128 v[196:199], v155 offset:53248
	ds_read_b128 v[200:203], v155 offset:54272
	ds_read_b128 v[204:207], v155 offset:55296
	ds_read_b128 v[208:211], v155 offset:56320
	global_load_lds_dwordx4 v[212:213], off
	s_add_i32 m0, s40, 0x2000
	s_add_u32 s40, s48, 0x158080
	v_lshl_add_u64 v[212:213], v[214:215], 0, s[20:21]
	s_addc_u32 s41, s49, 0
	s_add_i32 s48, s79, s35
	global_load_lds_dwordx4 v[212:213], off
	v_lshl_add_u64 v[212:213], s[40:41], 0, v[132:133]
	s_mov_b32 m0, s48
	s_nop 0
	global_load_lds_dwordx4 v[212:213], off
	v_lshl_add_u64 v[212:213], s[40:41], 0, v[128:129]
	s_add_i32 m0, s48, 0x2000
	s_nop 0
	global_load_lds_dwordx4 v[212:213], off
	v_lshl_add_u64 v[212:213], v[216:217], 0, s[20:21]
	s_mov_b32 m0, s58
	s_nop 0
	global_load_lds_dwordx4 v[212:213], off
	v_lshl_add_u64 v[212:213], v[218:219], 0, s[20:21]
	s_mov_b32 m0, s59
	s_nop 0
	global_load_lds_dwordx4 v[212:213], off
	s_waitcnt vmcnt(8)
	s_waitcnt lgkmcnt(0)
	s_barrier
	s_setprio 1
	s_waitcnt lgkmcnt(0)
	v_mfma_i32_16x16x64_i8 v[60:63], v[144:147], v[180:183], v[60:63]
	v_mfma_i32_16x16x64_i8 v[56:59], v[156:159], v[180:183], v[56:59]
	v_mfma_i32_16x16x64_i8 v[44:47], v[144:147], v[188:191], v[44:47]
	v_mfma_i32_16x16x64_i8 v[40:43], v[156:159], v[188:191], v[40:43]
	v_mfma_i32_16x16x64_i8 v[28:31], v[144:147], v[196:199], v[28:31]
	v_mfma_i32_16x16x64_i8 v[24:27], v[156:159], v[196:199], v[24:27]
	v_mfma_i32_16x16x64_i8 v[12:15], v[144:147], v[204:207], v[12:15]
	v_mfma_i32_16x16x64_i8 v[8:11], v[156:159], v[204:207], v[8:11]
	v_mfma_i32_16x16x64_i8 v[60:63], v[148:151], v[184:187], v[60:63]
	v_mfma_i32_16x16x64_i8 v[56:59], v[160:163], v[184:187], v[56:59]
	v_mfma_i32_16x16x64_i8 v[44:47], v[148:151], v[192:195], v[44:47]
	v_mfma_i32_16x16x64_i8 v[40:43], v[160:163], v[192:195], v[40:43]
	v_mfma_i32_16x16x64_i8 v[28:31], v[148:151], v[200:203], v[28:31]
	v_mfma_i32_16x16x64_i8 v[24:27], v[160:163], v[200:203], v[24:27]
	v_mfma_i32_16x16x64_i8 v[12:15], v[148:151], v[208:211], v[12:15]
	v_mfma_i32_16x16x64_i8 v[8:11], v[160:163], v[208:211], v[8:11]
	s_setprio 0
	s_setprio 1
	v_mfma_i32_16x16x64_i8 v[52:55], v[164:167], v[180:183], v[52:55]
	v_mfma_i32_16x16x64_i8 v[48:51], v[172:175], v[180:183], v[48:51]
	v_mfma_i32_16x16x64_i8 v[36:39], v[164:167], v[188:191], v[36:39]
	v_mfma_i32_16x16x64_i8 v[32:35], v[172:175], v[188:191], v[32:35]
	v_mfma_i32_16x16x64_i8 v[20:23], v[164:167], v[196:199], v[20:23]
	v_mfma_i32_16x16x64_i8 v[16:19], v[172:175], v[196:199], v[16:19]
	v_mfma_i32_16x16x64_i8 v[4:7], v[164:167], v[204:207], v[4:7]
	v_mfma_i32_16x16x64_i8 v[0:3], v[172:175], v[204:207], v[0:3]
	v_mfma_i32_16x16x64_i8 v[52:55], v[168:171], v[184:187], v[52:55]
	v_mfma_i32_16x16x64_i8 v[48:51], v[176:179], v[184:187], v[48:51]
	v_mfma_i32_16x16x64_i8 v[36:39], v[168:171], v[192:195], v[36:39]
	v_mfma_i32_16x16x64_i8 v[32:35], v[176:179], v[192:195], v[32:35]
	v_mfma_i32_16x16x64_i8 v[20:23], v[168:171], v[200:203], v[20:23]
	v_mfma_i32_16x16x64_i8 v[16:19], v[176:179], v[200:203], v[16:19]
	v_mfma_i32_16x16x64_i8 v[4:7], v[168:171], v[208:211], v[4:7]
	v_mfma_i32_16x16x64_i8 v[0:3], v[176:179], v[208:211], v[0:3]
	s_setprio 0
	s_barrier
	s_add_i32 s77, s77, 2
	s_add_u32 s75, s75, 0x100
	s_addc_u32 s76, s76, 0
	s_cmpk_gt_u32 s77, 0x53
	s_mov_b64 s[40:41], s[46:47]
	s_cbranch_scc0 .LBB0_978
.Lpost_p7:
	s_and_b64 vcc, exec, s[22:23]
	s_cbranch_vccz .LBB0_981
	s_barrier
.LBB0_981:
	s_mov_b32 s40, 0
	v_cvt_f32_i32_e32 v175, v125
	v_mbcnt_lo_u32_b32 v144, -1, s40
	v_mbcnt_hi_u32_b32 v148, -1, v144
	s_lshl_b32 s40, s74, 8
	v_ashrrev_i32_e32 v144, 1, v148
	s_or_b32 s40, s40, s57
	v_and_b32_e32 v144, -8, v144
	v_add_u32_e32 v146, s40, v144
	s_lshl_b32 s40, s73, 8
	s_add_i32 s40, s40, s56
	v_ashrrev_i32_e32 v147, 31, v146
	v_and_or_b32 v148, v148, 15, s40
	v_lshl_add_u64 v[144:145], v[146:147], 2, s[18:19]
	v_ashrrev_i32_e32 v149, 31, v148
	global_load_dwordx4 v[156:159], v[144:145], off offset:16
	global_load_dwordx4 v[160:163], v[144:145], off
	global_load_dwordx4 v[164:167], v[144:145], off offset:528
	global_load_dwordx4 v[168:171], v[144:145], off offset:512
	v_lshl_add_u64 v[144:145], v[148:149], 2, s[16:17]
	global_load_dword v224, v[144:145], off offset:64
	global_load_dword v226, v[144:145], off offset:128
	global_load_dword v228, v[144:145], off offset:192
	global_load_dword v230, v[144:145], off offset:512
	global_load_dword v232, v[144:145], off offset:576
	global_load_dword v234, v[144:145], off offset:640
	global_load_dword v236, v[144:145], off offset:704
	global_load_dword v172, v[144:145], off
	v_cvt_f32_i32_e32 v174, v124
	v_cvt_f32_i32_e32 v177, v127
	v_cvt_f32_i32_e32 v176, v126
	v_cvt_f32_i32_e32 v187, v113
	v_cvt_f32_i32_e32 v186, v112
	v_lshlrev_b64 v[112:113], 13, v[148:149]
	v_cvt_f32_i32_e32 v179, v121
	v_cvt_f32_i32_e32 v178, v120
	v_cvt_f32_i32_e32 v181, v123
	v_cvt_f32_i32_e32 v180, v122
	v_lshl_add_u64 v[112:113], s[12:13], 0, v[112:113]
	v_lshlrev_b64 v[150:151], 1, v[146:147]
	v_cvt_f32_i32_e32 v183, v117
	v_cvt_f32_i32_e32 v182, v116
	v_cvt_f32_i32_e32 v185, v119
	v_cvt_f32_i32_e32 v184, v118
	v_cvt_f32_i32_e32 v189, v115
	v_cvt_f32_i32_e32 v188, v114
	v_lshl_add_u64 v[120:121], v[112:113], 0, v[150:151]
	v_or_b32_e32 v190, 16, v148
	v_ashrrev_i32_e32 v191, 31, v190
	v_lshl_add_u64 v[192:193], v[190:191], 2, s[16:17]
	v_cvt_f32_i32_e32 v109, v109
	v_cvt_f32_i32_e32 v108, v108
	v_cvt_f32_i32_e32 v111, v111
	v_cvt_f32_i32_e32 v110, v110
	v_cvt_f32_i32_e32 v105, v105
	v_cvt_f32_i32_e32 v104, v104
	v_cvt_f32_i32_e32 v107, v107
	v_cvt_f32_i32_e32 v106, v106
	v_cvt_f32_i32_e32 v97, v97
	v_cvt_f32_i32_e32 v96, v96
	v_cvt_f32_i32_e32 v99, v99
	v_cvt_f32_i32_e32 v98, v98
	v_cvt_f32_i32_e32 v101, v101
	v_cvt_f32_i32_e32 v100, v100
	v_cvt_f32_i32_e32 v103, v103
	v_cvt_f32_i32_e32 v102, v102
	v_cvt_f32_i32_e32 v93, v93
	v_cvt_f32_i32_e32 v92, v92
	v_cvt_f32_i32_e32 v95, v95
	v_cvt_f32_i32_e32 v94, v94
	v_cvt_f32_i32_e32 v89, v89
	v_cvt_f32_i32_e32 v88, v88
	v_cvt_f32_i32_e32 v91, v91
	v_cvt_f32_i32_e32 v90, v90
	v_cvt_f32_i32_e32 v81, v81
	v_cvt_f32_i32_e32 v80, v80
	v_cvt_f32_i32_e32 v83, v83
	v_cvt_f32_i32_e32 v82, v82
	v_cvt_f32_i32_e32 v85, v85
	v_cvt_f32_i32_e32 v84, v84
	v_cvt_f32_i32_e32 v87, v87
	v_cvt_f32_i32_e32 v86, v86
	v_cvt_f32_i32_e32 v77, v77
	v_cvt_f32_i32_e32 v76, v76
	v_cvt_f32_i32_e32 v79, v79
	v_cvt_f32_i32_e32 v78, v78
	v_cvt_f32_i32_e32 v73, v73
	v_cvt_f32_i32_e32 v72, v72
	v_cvt_f32_i32_e32 v75, v75
	v_cvt_f32_i32_e32 v74, v74
	v_cvt_f32_i32_e32 v65, v65
	v_cvt_f32_i32_e32 v64, v64
	v_cvt_f32_i32_e32 v67, v67
	v_cvt_f32_i32_e32 v66, v66
	v_cvt_f32_i32_e32 v69, v69
	v_cvt_f32_i32_e32 v68, v68
	v_cvt_f32_i32_e32 v71, v71
	v_cvt_f32_i32_e32 v70, v70
	v_cvt_f32_i32_e32 v61, v61
	v_cvt_f32_i32_e32 v60, v60
	v_cvt_f32_i32_e32 v63, v63
	v_cvt_f32_i32_e32 v62, v62
	v_cvt_f32_i32_e32 v57, v57
	s_waitcnt vmcnt(0)
	v_pk_mul_f32 v[114:115], v[158:159], s[24:25] op_sel_hi:[1,0]
	v_pk_mul_f32 v[112:113], v[162:163], s[24:25] op_sel_hi:[1,0]
	v_pk_mul_f32 v[122:123], v[160:161], s[24:25] op_sel_hi:[1,0]
	v_pk_mul_f32 v[124:125], v[156:157], s[24:25] op_sel_hi:[1,0]
	v_pk_mul_f32 v[156:157], v[122:123], v[172:173] op_sel_hi:[1,0]
	v_pk_mul_f32 v[158:159], v[112:113], v[172:173] op_sel_hi:[1,0]
	v_pk_mul_f32 v[116:117], v[170:171], s[24:25] op_sel_hi:[1,0]
	v_pk_mul_f32 v[126:127], v[168:169], s[24:25] op_sel_hi:[1,0]
	v_pk_mul_f32 v[118:119], v[166:167], s[24:25] op_sel_hi:[1,0]
	v_pk_mul_f32 v[146:147], v[164:165], s[24:25] op_sel_hi:[1,0]
	v_pk_mul_f32 v[160:161], v[124:125], v[172:173] op_sel_hi:[1,0]
	v_pk_mul_f32 v[162:163], v[114:115], v[172:173] op_sel_hi:[1,0]
	v_pk_mul_f32 v[158:159], v[158:159], v[176:177]
	v_pk_mul_f32 v[156:157], v[156:157], v[174:175]
	v_pk_mul_f32 v[164:165], v[126:127], v[172:173] op_sel_hi:[1,0]
	v_pk_mul_f32 v[166:167], v[116:117], v[172:173] op_sel_hi:[1,0]
	v_pk_mul_f32 v[168:169], v[146:147], v[172:173] op_sel_hi:[1,0]
	v_pk_mul_f32 v[170:171], v[118:119], v[172:173] op_sel_hi:[1,0]
	v_pk_mul_f32 v[162:163], v[162:163], v[180:181]
	v_pk_mul_f32 v[160:161], v[160:161], v[178:179]
	v_cvt_pk_bf16_f32 v156, v156, v157
	v_cvt_pk_bf16_f32 v157, v158, v159
	v_pk_mul_f32 v[166:167], v[166:167], v[184:185]
	v_cvt_pk_bf16_f32 v158, v160, v161
	v_cvt_pk_bf16_f32 v159, v162, v163
	v_pk_mul_f32 v[164:165], v[164:165], v[182:183]
	v_pk_mul_f32 v[170:171], v[170:171], v[188:189]
	v_pk_mul_f32 v[168:169], v[168:169], v[186:187]
	global_store_dwordx4 v[120:121], v[156:159], off
	v_lshlrev_b64 v[160:161], 13, v[190:191]
	v_lshl_add_u64 v[160:161], s[12:13], 0, v[160:161]
	v_cvt_pk_bf16_f32 v156, v164, v165
	v_cvt_pk_bf16_f32 v157, v166, v167
	v_cvt_pk_bf16_f32 v158, v168, v169
	v_cvt_pk_bf16_f32 v159, v170, v171
	global_store_dwordx4 v[120:121], v[156:159], off offset:256
	s_nop 0
	v_lshl_add_u64 v[160:161], v[160:161], 0, v[150:151]
	v_or_b32_e32 v158, 32, v148
	v_ashrrev_i32_e32 v159, 31, v158
	v_lshl_add_u64 v[162:163], v[158:159], 2, s[16:17]
	v_cvt_f32_i32_e32 v56, v56
	v_cvt_f32_i32_e32 v59, v59
	v_cvt_f32_i32_e32 v58, v58
	v_cvt_f32_i32_e32 v49, v49
	v_cvt_f32_i32_e32 v48, v48
	v_cvt_f32_i32_e32 v51, v51
	v_cvt_f32_i32_e32 v50, v50
	v_cvt_f32_i32_e32 v53, v53
	v_cvt_f32_i32_e32 v52, v52
	v_cvt_f32_i32_e32 v55, v55
	v_cvt_f32_i32_e32 v54, v54
	v_cvt_f32_i32_e32 v45, v45
	v_cvt_f32_i32_e32 v44, v44
	v_cvt_f32_i32_e32 v47, v47
	v_cvt_f32_i32_e32 v46, v46
	v_cvt_f32_i32_e32 v41, v41
	v_cvt_f32_i32_e32 v40, v40
	v_cvt_f32_i32_e32 v43, v43
	v_cvt_f32_i32_e32 v42, v42
	v_cvt_f32_i32_e32 v33, v33
	v_cvt_f32_i32_e32 v32, v32
	v_cvt_f32_i32_e32 v35, v35
	v_cvt_f32_i32_e32 v34, v34
	v_cvt_f32_i32_e32 v37, v37
	v_cvt_f32_i32_e32 v36, v36
	v_cvt_f32_i32_e32 v39, v39
	v_cvt_f32_i32_e32 v38, v38
	v_cvt_f32_i32_e32 v29, v29
	v_cvt_f32_i32_e32 v28, v28
	v_cvt_f32_i32_e32 v31, v31
	v_cvt_f32_i32_e32 v30, v30
	v_cvt_f32_i32_e32 v25, v25
	v_cvt_f32_i32_e32 v24, v24
	v_cvt_f32_i32_e32 v27, v27
	v_cvt_f32_i32_e32 v26, v26
	v_cvt_f32_i32_e32 v17, v17
	v_cvt_f32_i32_e32 v16, v16
	v_cvt_f32_i32_e32 v19, v19
	v_cvt_f32_i32_e32 v18, v18
	v_cvt_f32_i32_e32 v21, v21
	v_cvt_f32_i32_e32 v20, v20
	v_cvt_f32_i32_e32 v23, v23
	v_cvt_f32_i32_e32 v22, v22
	v_cvt_f32_i32_e32 v13, v13
	v_cvt_f32_i32_e32 v12, v12
	v_cvt_f32_i32_e32 v15, v15
	v_cvt_f32_i32_e32 v14, v14
	v_cvt_f32_i32_e32 v9, v9
	v_cvt_f32_i32_e32 v8, v8
	v_cvt_f32_i32_e32 v11, v11
	v_cvt_f32_i32_e32 v10, v10
	v_cvt_f32_i32_e32 v1, v1
	v_cvt_f32_i32_e32 v0, v0
	v_cvt_f32_i32_e32 v3, v3
	v_cvt_f32_i32_e32 v2, v2
	v_cvt_f32_i32_e32 v5, v5
	v_cvt_f32_i32_e32 v4, v4
	v_cvt_f32_i32_e32 v7, v7
	v_cvt_f32_i32_e32 v6, v6
	s_nop 0
	v_pk_mul_f32 v[164:165], v[122:123], v[224:225] op_sel_hi:[1,0]
	v_pk_mul_f32 v[166:167], v[112:113], v[224:225] op_sel_hi:[1,0]
	v_pk_mul_f32 v[168:169], v[124:125], v[224:225] op_sel_hi:[1,0]
	v_pk_mul_f32 v[170:171], v[114:115], v[224:225] op_sel_hi:[1,0]
	v_pk_mul_f32 v[172:173], v[126:127], v[224:225] op_sel_hi:[1,0]
	v_pk_mul_f32 v[174:175], v[116:117], v[224:225] op_sel_hi:[1,0]
	v_pk_mul_f32 v[176:177], v[146:147], v[224:225] op_sel_hi:[1,0]
	v_pk_mul_f32 v[156:157], v[118:119], v[224:225] op_sel_hi:[1,0]
	v_pk_mul_f32 v[110:111], v[166:167], v[110:111]
	v_pk_mul_f32 v[108:109], v[164:165], v[108:109]
	v_pk_mul_f32 v[106:107], v[170:171], v[106:107]
	v_pk_mul_f32 v[104:105], v[168:169], v[104:105]
	v_pk_mul_f32 v[156:157], v[156:157], v[98:99]
	v_pk_mul_f32 v[164:165], v[176:177], v[96:97]
	v_cvt_pk_bf16_f32 v96, v108, v109
	v_cvt_pk_bf16_f32 v97, v110, v111
	v_cvt_pk_bf16_f32 v98, v104, v105
	v_cvt_pk_bf16_f32 v99, v106, v107
	v_pk_mul_f32 v[102:103], v[174:175], v[102:103]
	v_pk_mul_f32 v[100:101], v[172:173], v[100:101]
	global_store_dwordx4 v[160:161], v[96:99], off
	s_nop 1
	v_cvt_pk_bf16_f32 v96, v100, v101
	v_cvt_pk_bf16_f32 v97, v102, v103
	v_cvt_pk_bf16_f32 v98, v164, v165
	v_cvt_pk_bf16_f32 v99, v156, v157
	global_store_dwordx4 v[160:161], v[96:99], off offset:256
	s_nop 0
	v_lshlrev_b64 v[100:101], 13, v[158:159]
	v_or_b32_e32 v98, 48, v148
	v_lshl_add_u64 v[100:101], s[12:13], 0, v[100:101]
	v_ashrrev_i32_e32 v99, 31, v98
	v_lshl_add_u64 v[100:101], v[100:101], 0, v[150:151]
	v_lshl_add_u64 v[102:103], v[98:99], 2, s[16:17]
	s_nop 0
	v_pk_mul_f32 v[104:105], v[122:123], v[226:227] op_sel_hi:[1,0]
	v_pk_mul_f32 v[106:107], v[112:113], v[226:227] op_sel_hi:[1,0]
	v_pk_mul_f32 v[108:109], v[124:125], v[226:227] op_sel_hi:[1,0]
	v_pk_mul_f32 v[110:111], v[114:115], v[226:227] op_sel_hi:[1,0]
	v_pk_mul_f32 v[148:149], v[126:127], v[226:227] op_sel_hi:[1,0]
	v_pk_mul_f32 v[156:157], v[116:117], v[226:227] op_sel_hi:[1,0]
	v_pk_mul_f32 v[158:159], v[146:147], v[226:227] op_sel_hi:[1,0]
	v_pk_mul_f32 v[96:97], v[118:119], v[226:227] op_sel_hi:[1,0]
	v_pk_mul_f32 v[94:95], v[106:107], v[94:95]
	v_pk_mul_f32 v[92:93], v[104:105], v[92:93]
	v_pk_mul_f32 v[90:91], v[110:111], v[90:91]
	v_pk_mul_f32 v[88:89], v[108:109], v[88:89]
	v_pk_mul_f32 v[96:97], v[96:97], v[82:83]
	v_pk_mul_f32 v[104:105], v[158:159], v[80:81]
	v_cvt_pk_bf16_f32 v80, v92, v93
	v_cvt_pk_bf16_f32 v81, v94, v95
	v_cvt_pk_bf16_f32 v82, v88, v89
	v_cvt_pk_bf16_f32 v83, v90, v91
	v_pk_mul_f32 v[86:87], v[156:157], v[86:87]
	v_pk_mul_f32 v[84:85], v[148:149], v[84:85]
	global_store_dwordx4 v[100:101], v[80:83], off
	s_nop 1
	v_cvt_pk_bf16_f32 v80, v84, v85
	v_cvt_pk_bf16_f32 v81, v86, v87
	v_cvt_pk_bf16_f32 v82, v104, v105
	v_cvt_pk_bf16_f32 v83, v96, v97
	global_store_dwordx4 v[100:101], v[80:83], off offset:256
	s_nop 0
	s_nop 0
	v_pk_mul_f32 v[84:85], v[122:123], v[228:229] op_sel_hi:[1,0]
	v_lshlrev_b64 v[82:83], 13, v[98:99]
	v_lshl_add_u64 v[82:83], s[12:13], 0, v[82:83]
	v_pk_mul_f32 v[86:87], v[112:113], v[228:229] op_sel_hi:[1,0]
	v_pk_mul_f32 v[88:89], v[124:125], v[228:229] op_sel_hi:[1,0]
	v_pk_mul_f32 v[90:91], v[114:115], v[228:229] op_sel_hi:[1,0]
	v_pk_mul_f32 v[92:93], v[126:127], v[228:229] op_sel_hi:[1,0]
	v_pk_mul_f32 v[94:95], v[116:117], v[228:229] op_sel_hi:[1,0]
	v_pk_mul_f32 v[96:97], v[146:147], v[228:229] op_sel_hi:[1,0]
	v_pk_mul_f32 v[80:81], v[118:119], v[228:229] op_sel_hi:[1,0]
	v_lshl_add_u64 v[82:83], v[82:83], 0, v[150:151]
	v_pk_mul_f32 v[78:79], v[86:87], v[78:79]
	v_pk_mul_f32 v[76:77], v[84:85], v[76:77]
	v_pk_mul_f32 v[74:75], v[90:91], v[74:75]
	v_pk_mul_f32 v[72:73], v[88:89], v[72:73]
	v_pk_mul_f32 v[80:81], v[80:81], v[66:67]
	v_pk_mul_f32 v[84:85], v[96:97], v[64:65]
	v_cvt_pk_bf16_f32 v64, v76, v77
	v_cvt_pk_bf16_f32 v65, v78, v79
	v_cvt_pk_bf16_f32 v66, v72, v73
	v_cvt_pk_bf16_f32 v67, v74, v75
	v_pk_mul_f32 v[70:71], v[94:95], v[70:71]
	v_pk_mul_f32 v[68:69], v[92:93], v[68:69]
	global_store_dwordx4 v[82:83], v[64:67], off
	s_nop 1
	v_cvt_pk_bf16_f32 v64, v68, v69
	v_cvt_pk_bf16_f32 v65, v70, v71
	v_cvt_pk_bf16_f32 v66, v84, v85
	v_cvt_pk_bf16_f32 v67, v80, v81
	global_store_dwordx4 v[82:83], v[64:67], off offset:256
	s_nop 0
	v_add_co_u32_e32 v68, vcc, s63, v120
	v_lshl_add_u64 v[66:67], v[120:121], 0, s[26:27]
	s_nop 0
	v_addc_co_u32_e32 v69, vcc, 0, v121, vcc
	s_nop 0
	v_pk_mul_f32 v[70:71], v[122:123], v[230:231] op_sel_hi:[1,0]
	v_pk_mul_f32 v[72:73], v[112:113], v[230:231] op_sel_hi:[1,0]
	v_pk_mul_f32 v[74:75], v[124:125], v[230:231] op_sel_hi:[1,0]
	v_pk_mul_f32 v[76:77], v[114:115], v[230:231] op_sel_hi:[1,0]
	v_pk_mul_f32 v[78:79], v[126:127], v[230:231] op_sel_hi:[1,0]
	v_pk_mul_f32 v[80:81], v[116:117], v[230:231] op_sel_hi:[1,0]
	v_pk_mul_f32 v[82:83], v[146:147], v[230:231] op_sel_hi:[1,0]
	v_pk_mul_f32 v[64:65], v[118:119], v[230:231] op_sel_hi:[1,0]
	v_pk_mul_f32 v[62:63], v[72:73], v[62:63]
	v_pk_mul_f32 v[60:61], v[70:71], v[60:61]
	v_pk_mul_f32 v[58:59], v[76:77], v[58:59]
	v_pk_mul_f32 v[56:57], v[74:75], v[56:57]
	v_pk_mul_f32 v[64:65], v[64:65], v[50:51]
	v_pk_mul_f32 v[70:71], v[82:83], v[48:49]
	v_cvt_pk_bf16_f32 v48, v60, v61
	v_cvt_pk_bf16_f32 v49, v62, v63
	v_cvt_pk_bf16_f32 v50, v56, v57
	v_cvt_pk_bf16_f32 v51, v58, v59
	v_pk_mul_f32 v[54:55], v[80:81], v[54:55]
	v_pk_mul_f32 v[52:53], v[78:79], v[52:53]
	global_store_dwordx4 v[68:69], v[48:51], off
	s_nop 1
	v_cvt_pk_bf16_f32 v48, v52, v53
	v_cvt_pk_bf16_f32 v49, v54, v55
	v_cvt_pk_bf16_f32 v50, v70, v71
	v_cvt_pk_bf16_f32 v51, v64, v65
	global_store_dwordx4 v[66:67], v[48:51], off offset:256
	s_nop 0
	v_add_co_u32_e32 v52, vcc, s65, v120
	v_lshl_add_u64 v[50:51], v[120:121], 0, s[28:29]
	s_nop 0
	v_addc_co_u32_e32 v53, vcc, 0, v121, vcc
	s_nop 0
	v_pk_mul_f32 v[54:55], v[122:123], v[232:233] op_sel_hi:[1,0]
	v_pk_mul_f32 v[56:57], v[112:113], v[232:233] op_sel_hi:[1,0]
	v_pk_mul_f32 v[58:59], v[124:125], v[232:233] op_sel_hi:[1,0]
	v_pk_mul_f32 v[60:61], v[114:115], v[232:233] op_sel_hi:[1,0]
	v_pk_mul_f32 v[62:63], v[126:127], v[232:233] op_sel_hi:[1,0]
	v_pk_mul_f32 v[64:65], v[116:117], v[232:233] op_sel_hi:[1,0]
	v_pk_mul_f32 v[66:67], v[146:147], v[232:233] op_sel_hi:[1,0]
	v_pk_mul_f32 v[48:49], v[118:119], v[232:233] op_sel_hi:[1,0]
	v_pk_mul_f32 v[46:47], v[56:57], v[46:47]
	v_pk_mul_f32 v[44:45], v[54:55], v[44:45]
	v_pk_mul_f32 v[42:43], v[60:61], v[42:43]
	v_pk_mul_f32 v[40:41], v[58:59], v[40:41]
	v_pk_mul_f32 v[48:49], v[48:49], v[34:35]
	v_pk_mul_f32 v[54:55], v[66:67], v[32:33]
	v_cvt_pk_bf16_f32 v32, v44, v45
	v_cvt_pk_bf16_f32 v33, v46, v47
	v_cvt_pk_bf16_f32 v34, v40, v41
	v_cvt_pk_bf16_f32 v35, v42, v43
	v_pk_mul_f32 v[38:39], v[64:65], v[38:39]
	v_pk_mul_f32 v[36:37], v[62:63], v[36:37]
	global_store_dwordx4 v[52:53], v[32:35], off
	s_nop 1
	v_cvt_pk_bf16_f32 v32, v36, v37
	v_cvt_pk_bf16_f32 v33, v38, v39
	v_cvt_pk_bf16_f32 v34, v54, v55
	v_cvt_pk_bf16_f32 v35, v48, v49
	global_store_dwordx4 v[50:51], v[32:35], off offset:256
	s_nop 0
	v_add_co_u32_e32 v36, vcc, s67, v120
	v_lshl_add_u64 v[34:35], v[120:121], 0, s[30:31]
	s_nop 0
	v_addc_co_u32_e32 v37, vcc, 0, v121, vcc
	s_and_b64 vcc, exec, s[6:7]
	s_nop 0
	v_pk_mul_f32 v[38:39], v[122:123], v[234:235] op_sel_hi:[1,0]
	v_pk_mul_f32 v[40:41], v[112:113], v[234:235] op_sel_hi:[1,0]
	v_pk_mul_f32 v[42:43], v[124:125], v[234:235] op_sel_hi:[1,0]
	v_pk_mul_f32 v[44:45], v[114:115], v[234:235] op_sel_hi:[1,0]
	v_pk_mul_f32 v[46:47], v[126:127], v[234:235] op_sel_hi:[1,0]
	v_pk_mul_f32 v[48:49], v[116:117], v[234:235] op_sel_hi:[1,0]
	v_pk_mul_f32 v[50:51], v[146:147], v[234:235] op_sel_hi:[1,0]
	v_pk_mul_f32 v[32:33], v[118:119], v[234:235] op_sel_hi:[1,0]
	v_pk_mul_f32 v[30:31], v[40:41], v[30:31]
	v_pk_mul_f32 v[28:29], v[38:39], v[28:29]
	v_pk_mul_f32 v[26:27], v[44:45], v[26:27]
	v_pk_mul_f32 v[24:25], v[42:43], v[24:25]
	v_pk_mul_f32 v[32:33], v[32:33], v[18:19]
	v_pk_mul_f32 v[38:39], v[50:51], v[16:17]
	v_cvt_pk_bf16_f32 v16, v28, v29
	v_cvt_pk_bf16_f32 v17, v30, v31
	v_cvt_pk_bf16_f32 v18, v24, v25
	v_cvt_pk_bf16_f32 v19, v26, v27
	v_pk_mul_f32 v[22:23], v[48:49], v[22:23]
	v_pk_mul_f32 v[20:21], v[46:47], v[20:21]
	global_store_dwordx4 v[36:37], v[16:19], off
	s_nop 1
	v_cvt_pk_bf16_f32 v16, v20, v21
	v_cvt_pk_bf16_f32 v17, v22, v23
	v_cvt_pk_bf16_f32 v18, v38, v39
	v_cvt_pk_bf16_f32 v19, v32, v33
	global_store_dwordx4 v[34:35], v[16:19], off offset:256
	s_nop 0
	v_add_co_u32_e64 v20, s[6:7], s70, v120
	v_lshl_add_u64 v[18:19], v[120:121], 0, s[36:37]
	s_nop 0
	v_addc_co_u32_e64 v21, s[6:7], 0, v121, s[6:7]
	s_mov_b64 s[6:7], -1
	s_nop 0
	v_pk_mul_f32 v[22:23], v[122:123], v[236:237] op_sel_hi:[1,0]
	v_pk_mul_f32 v[24:25], v[112:113], v[236:237] op_sel_hi:[1,0]
	v_pk_mul_f32 v[26:27], v[124:125], v[236:237] op_sel_hi:[1,0]
	v_pk_mul_f32 v[28:29], v[114:115], v[236:237] op_sel_hi:[1,0]
	v_pk_mul_f32 v[30:31], v[126:127], v[236:237] op_sel_hi:[1,0]
	v_pk_mul_f32 v[32:33], v[116:117], v[236:237] op_sel_hi:[1,0]
	v_pk_mul_f32 v[34:35], v[146:147], v[236:237] op_sel_hi:[1,0]
	v_pk_mul_f32 v[16:17], v[118:119], v[236:237] op_sel_hi:[1,0]
	v_pk_mul_f32 v[14:15], v[24:25], v[14:15]
	v_pk_mul_f32 v[12:13], v[22:23], v[12:13]
	v_pk_mul_f32 v[10:11], v[28:29], v[10:11]
	v_pk_mul_f32 v[8:9], v[26:27], v[8:9]
	v_pk_mul_f32 v[16:17], v[16:17], v[2:3]
	v_pk_mul_f32 v[22:23], v[34:35], v[0:1]
	v_cvt_pk_bf16_f32 v0, v12, v13
	v_cvt_pk_bf16_f32 v1, v14, v15
	v_cvt_pk_bf16_f32 v2, v8, v9
	v_cvt_pk_bf16_f32 v3, v10, v11
	v_pk_mul_f32 v[6:7], v[32:33], v[6:7]
	v_pk_mul_f32 v[4:5], v[30:31], v[4:5]
	global_store_dwordx4 v[20:21], v[0:3], off
	s_nop 1
	v_cvt_pk_bf16_f32 v0, v4, v5
	v_cvt_pk_bf16_f32 v1, v6, v7
	v_cvt_pk_bf16_f32 v2, v22, v23
	v_cvt_pk_bf16_f32 v3, v16, v17
	global_store_dwordx4 v[18:19], v[0:3], off offset:256
	s_cbranch_vccnz .LBB0_970
	s_andn2_b64 vcc, exec, s[10:11]
	s_cbranch_vccnz .LBB0_969
	s_barrier
	s_branch .LBB0_969
